# weight-transpose items with folded norm gain (P0, P3, P5): 32 gain values requested in one batch instead of 32 serialized load+wait; plus QR loads ahead of the threshold search and early exit of the s
# speedup vs baseline: 1.0130x; 1.0039x over previous
; #define LAS __attribute__((address_space(3)))
; __device__ __forceinline__ void tr_load(const TrItem& t, float (&v)[32], int lane) {
;     const int n = lane & 31, kh = lane >> 5; const float* wp = t.W + (size_t)(t.k0 + kh) * t.ldw + t.n0 + (n < t.nvalid ? n : 0);
; #pragma unroll
;     for (int i = 0; i < 32; ++i) v[i] = wp[(size_t)(2 * i) * t.ldw];
; }
; __device__ __forceinline__ void tr_finish(const TrItem& t, const float (&v)[32], LAS float* scr, int lane) {
;     const int n = lane & 31, kh = lane >> 5;
; #pragma unroll
;     for (int i = 0; i < 32; ++i) { float x = n < t.nvalid ? v[i] : 0.f; if (t.g) x *= t.g[t.k0 + 2 * i + kh]; scr[(2 * i + kh) * 33 + n] = x; }
.LBB0_42:
	v_add_u32_e32 v8, s86, v1
	v_ashrrev_i32_e32 v9, 31, v8
	v_mul_lo_u32 v2, s20, v9
	v_mul_lo_u32 v7, s21, v8
	s_waitcnt vmcnt(45)
	v_mad_u64_u32 v[56:57], s[0:1], s20, v8, 0
	v_add3_u32 v57, v57, v2, v7
	v_lshl_add_u64 v[56:57], v[56:57], 2, s[4:5]
	s_ashr_i32 s7, s6, 31
	v_cndmask_b32_e64 v2, 0, v0, s[90:91]
	v_lshl_add_u64 v[56:57], s[6:7], 2, v[56:57]
	v_lshlrev_b32_e32 v2, 2, v2
	v_lshl_add_u64 v[56:57], v[56:57], 0, v[2:3]
	s_lshl_b64 s[0:1], s[20:21], 3
	v_lshl_add_u64 v[58:59], v[56:57], 0, s[0:1]
	v_lshl_add_u64 v[60:61], v[58:59], 0, s[0:1]
	v_lshl_add_u64 v[62:63], v[60:61], 0, s[0:1]
	v_lshl_add_u64 v[64:65], v[62:63], 0, s[0:1]
	v_lshl_add_u64 v[66:67], v[64:65], 0, s[0:1]
	v_lshl_add_u64 v[68:69], v[66:67], 0, s[0:1]
	v_lshl_add_u64 v[80:81], v[68:69], 0, s[0:1]
	global_load_dword v78, v[56:57], off
	global_load_dword v77, v[58:59], off
	global_load_dword v76, v[60:61], off
	global_load_dword v75, v[62:63], off
	global_load_dword v74, v[64:65], off
	global_load_dword v73, v[66:67], off
	global_load_dword v72, v[68:69], off
	global_load_dword v71, v[80:81], off
	v_lshl_add_u64 v[56:57], v[80:81], 0, s[0:1]
	global_load_dword v70, v[56:57], off
	v_lshl_add_u64 v[56:57], v[56:57], 0, s[0:1]
	global_load_dword v69, v[56:57], off
	v_lshl_add_u64 v[56:57], v[56:57], 0, s[0:1]
	global_load_dword v68, v[56:57], off
	v_lshl_add_u64 v[56:57], v[56:57], 0, s[0:1]
	global_load_dword v67, v[56:57], off
	v_lshl_add_u64 v[56:57], v[56:57], 0, s[0:1]
	global_load_dword v66, v[56:57], off
	v_lshl_add_u64 v[56:57], v[56:57], 0, s[0:1]
	global_load_dword v65, v[56:57], off
	v_lshl_add_u64 v[56:57], v[56:57], 0, s[0:1]
	global_load_dword v64, v[56:57], off
	v_lshl_add_u64 v[56:57], v[56:57], 0, s[0:1]
	global_load_dword v63, v[56:57], off
	v_lshl_add_u64 v[56:57], v[56:57], 0, s[0:1]
	global_load_dword v62, v[56:57], off
	v_lshl_add_u64 v[56:57], v[56:57], 0, s[0:1]
	global_load_dword v61, v[56:57], off
	v_lshl_add_u64 v[56:57], v[56:57], 0, s[0:1]
	global_load_dword v60, v[56:57], off
	v_lshl_add_u64 v[56:57], v[56:57], 0, s[0:1]
	global_load_dword v59, v[56:57], off
	v_lshl_add_u64 v[56:57], v[56:57], 0, s[0:1]
	v_lshl_add_u64 v[80:81], v[56:57], 0, s[0:1]
	global_load_dword v58, v[56:57], off
	s_nop 0
	global_load_dword v57, v[80:81], off
	v_lshl_add_u64 v[80:81], v[80:81], 0, s[0:1]
	global_load_dword v56, v[80:81], off
	v_lshl_add_u64 v[80:81], v[80:81], 0, s[0:1]
	global_load_dword v54, v[80:81], off
	v_lshl_add_u64 v[80:81], v[80:81], 0, s[0:1]
	global_load_dword v53, v[80:81], off
	v_lshl_add_u64 v[80:81], v[80:81], 0, s[0:1]
	global_load_dword v51, v[80:81], off
	v_lshl_add_u64 v[80:81], v[80:81], 0, s[0:1]
	global_load_dword v49, v[80:81], off
	v_lshl_add_u64 v[80:81], v[80:81], 0, s[0:1]
	global_load_dword v47, v[80:81], off
	v_lshl_add_u64 v[80:81], v[80:81], 0, s[0:1]
	global_load_dword v44, v[80:81], off
	v_lshl_add_u64 v[80:81], v[80:81], 0, s[0:1]
	global_load_dword v42, v[80:81], off
	v_lshl_add_u64 v[80:81], v[80:81], 0, s[0:1]
	global_load_dword v39, v[80:81], off
	v_lshl_add_u64 v[80:81], v[80:81], 0, s[0:1]
	global_load_dword v37, v[80:81], off
	s_cmp_lg_u64 s[82:83], 0
	v_add_u32_e32 v10, s28, v1
	v_cmp_gt_u32_e64 s[6:7], s29, v0
	s_cselect_b64 s[0:1], -1, 0
	s_cmp_eq_u64 s[82:83], 0
	s_waitcnt vmcnt(62)
	v_cndmask_b32_e64 v2, 0, v11, s[6:7]
	v_ashrrev_i32_e32 v11, 31, v10
	s_cbranch_scc1 .LBB0_44
	v_lshl_add_u64 v[80:81], v[10:11], 2, s[82:83]
	global_load_dword v150, v[80:81], off
	global_load_dword v151, v[80:81], off offset:8
	global_load_dword v152, v[80:81], off offset:16
	global_load_dword v153, v[80:81], off offset:24
	global_load_dword v154, v[80:81], off offset:32
	global_load_dword v155, v[80:81], off offset:40
	global_load_dword v156, v[80:81], off offset:48
	global_load_dword v157, v[80:81], off offset:56
	global_load_dword v158, v[80:81], off offset:64
	global_load_dword v159, v[80:81], off offset:72
	global_load_dword v160, v[80:81], off offset:80
	global_load_dword v161, v[80:81], off offset:88
	global_load_dword v162, v[80:81], off offset:96
	global_load_dword v163, v[80:81], off offset:104
	global_load_dword v164, v[80:81], off offset:112
	global_load_dword v165, v[80:81], off offset:120
	global_load_dword v166, v[80:81], off offset:128
	global_load_dword v167, v[80:81], off offset:136
	global_load_dword v168, v[80:81], off offset:144
	global_load_dword v169, v[80:81], off offset:152
	global_load_dword v170, v[80:81], off offset:160
	global_load_dword v171, v[80:81], off offset:168
	global_load_dword v172, v[80:81], off offset:176
	global_load_dword v173, v[80:81], off offset:184
	global_load_dword v174, v[80:81], off offset:192
	global_load_dword v175, v[80:81], off offset:200
	global_load_dword v176, v[80:81], off offset:208
	global_load_dword v177, v[80:81], off offset:216
	global_load_dword v178, v[80:81], off offset:224
	global_load_dword v179, v[80:81], off offset:232
	global_load_dword v180, v[80:81], off offset:240
	global_load_dword v181, v[80:81], off offset:248
	s_waitcnt vmcnt(0)
	v_mul_f32_e32 v2, v2, v150
.LBB0_44:
	ds_write_b32 v15, v2
	v_cndmask_b32_e64 v2, 0, 1, s[0:1]
	v_cmp_ne_u32_e64 s[4:5], 1, v2
	s_andn2_b64 vcc, exec, s[0:1]
	v_cndmask_b32_e64 v2, 0, v55, s[6:7]
	s_cbranch_vccnz .LBB0_46
	v_lshl_add_u64 v[80:81], v[10:11], 2, s[82:83]
	v_mul_f32_e32 v2, v2, v151
.LBB0_46:
	ds_write_b32 v15, v2 offset:264
	s_and_b64 vcc, exec, s[4:5]
	s_waitcnt vmcnt(61)
	v_cndmask_b32_e64 v2, 0, v52, s[6:7]
	s_cbranch_vccnz .LBB0_48
	v_lshl_add_u64 v[80:81], v[10:11], 2, s[82:83]
	v_mul_f32_e32 v2, v2, v152
; #define LAS __attribute__((address_space(3)))
; #define LDS_WAIT() asm volatile("s_waitcnt lgkmcnt(0)" ::: "memory")
; __device__ __forceinline__ void tr_finish(const TrItem& t, const float (&v)[32], LAS float* scr, int lane) {
;     const int n = lane & 31, kh = lane >> 5;
; #pragma unroll
;     for (int i = 0; i < 32; ++i) { float x = n < t.nvalid ? v[i] : 0.f; if (t.g) x *= t.g[t.k0 + 2 * i + kh]; scr[(2 * i + kh) * 33 + n] = x; }
;     LDS_WAIT(); asm volatile("" ::: "memory");
.LBB0_48:
	ds_write_b32 v15, v2 offset:528
	s_and_b64 vcc, exec, s[4:5]
	s_waitcnt vmcnt(60)
	v_cndmask_b32_e64 v2, 0, v50, s[6:7]
	s_cbranch_vccnz .LBB0_50
	v_lshl_add_u64 v[80:81], v[10:11], 2, s[82:83]
	v_mul_f32_e32 v2, v2, v153
.LBB0_50:
	ds_write_b32 v15, v2 offset:792
	s_and_b64 vcc, exec, s[4:5]
	s_waitcnt vmcnt(59)
	v_cndmask_b32_e64 v2, 0, v48, s[6:7]
	s_cbranch_vccnz .LBB0_52
	v_lshl_add_u64 v[80:81], v[10:11], 2, s[82:83]
	v_mul_f32_e32 v2, v2, v154
.LBB0_52:
	ds_write_b32 v15, v2 offset:1056
	s_and_b64 vcc, exec, s[4:5]
	s_waitcnt vmcnt(58)
	v_cndmask_b32_e64 v2, 0, v45, s[6:7]
	s_cbranch_vccnz .LBB0_54
	v_lshl_add_u64 v[80:81], v[10:11], 2, s[82:83]
	v_mul_f32_e32 v2, v2, v155
.LBB0_54:
	ds_write_b32 v15, v2 offset:1320
	s_and_b64 vcc, exec, s[4:5]
	s_waitcnt vmcnt(57)
	v_cndmask_b32_e64 v2, 0, v41, s[6:7]
	s_cbranch_vccnz .LBB0_56
	v_lshl_add_u64 v[80:81], v[10:11], 2, s[82:83]
	v_mul_f32_e32 v2, v2, v156
.LBB0_56:
	ds_write_b32 v15, v2 offset:1584
	s_and_b64 vcc, exec, s[4:5]
	s_waitcnt vmcnt(56)
	v_cndmask_b32_e64 v2, 0, v38, s[6:7]
	s_cbranch_vccnz .LBB0_58
	v_lshl_add_u64 v[80:81], v[10:11], 2, s[82:83]
	v_mul_f32_e32 v2, v2, v157
.LBB0_58:
	ds_write_b32 v15, v2 offset:1848
	s_and_b64 vcc, exec, s[4:5]
	s_waitcnt vmcnt(55)
	v_cndmask_b32_e64 v2, 0, v46, s[6:7]
	s_cbranch_vccnz .LBB0_60
	v_lshl_add_u64 v[80:81], v[10:11], 2, s[82:83]
	v_mul_f32_e32 v2, v2, v158
.LBB0_60:
	ds_write_b32 v15, v2 offset:2112
	s_and_b64 vcc, exec, s[4:5]
	s_waitcnt vmcnt(54)
	v_cndmask_b32_e64 v2, 0, v43, s[6:7]
	s_cbranch_vccnz .LBB0_62
	v_lshl_add_u64 v[80:81], v[10:11], 2, s[82:83]
	v_mul_f32_e32 v2, v2, v159
.LBB0_62:
	ds_write_b32 v15, v2 offset:2376
	s_and_b64 vcc, exec, s[4:5]
	s_waitcnt vmcnt(53)
	v_cndmask_b32_e64 v2, 0, v40, s[6:7]
	s_cbranch_vccnz .LBB0_64
	v_lshl_add_u64 v[40:41], v[10:11], 2, s[82:83]
	v_mul_f32_e32 v2, v2, v160
.LBB0_64:
	ds_write_b32 v15, v2 offset:2640
	s_and_b64 vcc, exec, s[4:5]
	s_waitcnt vmcnt(52)
	v_cndmask_b32_e64 v2, 0, v36, s[6:7]
	s_cbranch_vccnz .LBB0_66
	v_lshl_add_u64 v[40:41], v[10:11], 2, s[82:83]
	v_mul_f32_e32 v2, v2, v161
.LBB0_66:
	ds_write_b32 v15, v2 offset:2904
	s_and_b64 vcc, exec, s[4:5]
	s_waitcnt vmcnt(51)
	v_cndmask_b32_e64 v2, 0, v35, s[6:7]
	s_cbranch_vccnz .LBB0_68
	v_lshl_add_u64 v[40:41], v[10:11], 2, s[82:83]
	v_mul_f32_e32 v2, v2, v162
.LBB0_68:
	ds_write_b32 v15, v2 offset:3168
	s_and_b64 vcc, exec, s[4:5]
	s_waitcnt vmcnt(50)
	v_cndmask_b32_e64 v2, 0, v33, s[6:7]
	s_cbranch_vccnz .LBB0_70
	v_lshl_add_u64 v[40:41], v[10:11], 2, s[82:83]
	v_mul_f32_e32 v2, v2, v163
.LBB0_70:
	ds_write_b32 v15, v2 offset:3432
	s_and_b64 vcc, exec, s[4:5]
	s_waitcnt vmcnt(49)
	v_cndmask_b32_e64 v2, 0, v31, s[6:7]
	s_cbranch_vccnz .LBB0_72
	v_lshl_add_u64 v[40:41], v[10:11], 2, s[82:83]
	v_mul_f32_e32 v2, v2, v164
.LBB0_72:
	ds_write_b32 v15, v2 offset:3696
	s_and_b64 vcc, exec, s[4:5]
	s_waitcnt vmcnt(48)
	v_cndmask_b32_e64 v2, 0, v29, s[6:7]
	s_cbranch_vccnz .LBB0_74
	v_lshl_add_u64 v[40:41], v[10:11], 2, s[82:83]
	v_mul_f32_e32 v2, v2, v165
.LBB0_74:
	ds_write_b32 v15, v2 offset:3960
	s_and_b64 vcc, exec, s[4:5]
	s_waitcnt vmcnt(47)
	v_cndmask_b32_e64 v2, 0, v34, s[6:7]
	s_cbranch_vccnz .LBB0_76
	v_lshl_add_u64 v[34:35], v[10:11], 2, s[82:83]
	v_mul_f32_e32 v2, v2, v166
.LBB0_76:
	ds_write_b32 v15, v2 offset:4224
	s_and_b64 vcc, exec, s[4:5]
	s_waitcnt vmcnt(46)
	v_cndmask_b32_e64 v2, 0, v32, s[6:7]
	s_cbranch_vccnz .LBB0_78
	v_lshl_add_u64 v[32:33], v[10:11], 2, s[82:83]
	v_mul_f32_e32 v2, v2, v167
.LBB0_78:
	ds_write_b32 v15, v2 offset:4488
	s_and_b64 vcc, exec, s[4:5]
	s_waitcnt vmcnt(45)
	v_cndmask_b32_e64 v2, 0, v30, s[6:7]
	s_cbranch_vccnz .LBB0_80
	v_lshl_add_u64 v[30:31], v[10:11], 2, s[82:83]
	v_mul_f32_e32 v2, v2, v168
.LBB0_80:
	ds_write_b32 v15, v2 offset:4752
	s_and_b64 vcc, exec, s[4:5]
	s_waitcnt vmcnt(44)
	v_cndmask_b32_e64 v2, 0, v28, s[6:7]
	s_cbranch_vccnz .LBB0_82
	v_lshl_add_u64 v[28:29], v[10:11], 2, s[82:83]
	v_mul_f32_e32 v2, v2, v169
.LBB0_82:
	ds_write_b32 v15, v2 offset:5016
	s_and_b64 vcc, exec, s[4:5]
	s_waitcnt vmcnt(43)
	v_cndmask_b32_e64 v2, 0, v27, s[6:7]
	s_cbranch_vccnz .LBB0_84
	v_lshl_add_u64 v[28:29], v[10:11], 2, s[82:83]
	v_mul_f32_e32 v2, v2, v170
.LBB0_84:
	ds_write_b32 v15, v2 offset:5280
	s_and_b64 vcc, exec, s[4:5]
	s_waitcnt vmcnt(42)
	v_cndmask_b32_e64 v2, 0, v25, s[6:7]
	s_cbranch_vccnz .LBB0_86
	v_lshl_add_u64 v[28:29], v[10:11], 2, s[82:83]
	v_mul_f32_e32 v2, v2, v171
.LBB0_86:
	ds_write_b32 v15, v2 offset:5544
	s_and_b64 vcc, exec, s[4:5]
	s_waitcnt vmcnt(41)
	v_cndmask_b32_e64 v2, 0, v23, s[6:7]
	s_cbranch_vccnz .LBB0_88
	v_lshl_add_u64 v[28:29], v[10:11], 2, s[82:83]
	v_mul_f32_e32 v2, v2, v172
.LBB0_88:
	ds_write_b32 v15, v2 offset:5808
	s_and_b64 vcc, exec, s[4:5]
	s_waitcnt vmcnt(40)
	v_cndmask_b32_e64 v2, 0, v21, s[6:7]
	s_cbranch_vccnz .LBB0_90
	v_lshl_add_u64 v[28:29], v[10:11], 2, s[82:83]
	v_mul_f32_e32 v2, v2, v173
.LBB0_90:
	ds_write_b32 v15, v2 offset:6072
	s_and_b64 vcc, exec, s[4:5]
	s_waitcnt vmcnt(39)
	v_cndmask_b32_e64 v2, 0, v26, s[6:7]
	s_cbranch_vccnz .LBB0_92
	v_lshl_add_u64 v[26:27], v[10:11], 2, s[82:83]
	v_mul_f32_e32 v2, v2, v174
.LBB0_92:
	ds_write_b32 v15, v2 offset:6336
	s_and_b64 vcc, exec, s[4:5]
	s_waitcnt vmcnt(38)
	v_cndmask_b32_e64 v2, 0, v24, s[6:7]
	s_cbranch_vccnz .LBB0_94
	v_lshl_add_u64 v[24:25], v[10:11], 2, s[82:83]
	v_mul_f32_e32 v2, v2, v175
.LBB0_94:
	ds_write_b32 v15, v2 offset:6600
	s_and_b64 vcc, exec, s[4:5]
	s_waitcnt vmcnt(37)
	v_cndmask_b32_e64 v2, 0, v22, s[6:7]
	s_cbranch_vccnz .LBB0_96
	v_lshl_add_u64 v[22:23], v[10:11], 2, s[82:83]
	v_mul_f32_e32 v2, v2, v176
.LBB0_96:
	ds_write_b32 v15, v2 offset:6864
	s_and_b64 vcc, exec, s[4:5]
	s_waitcnt vmcnt(36)
	v_cndmask_b32_e64 v2, 0, v20, s[6:7]
	s_cbranch_vccnz .LBB0_98
	v_lshl_add_u64 v[20:21], v[10:11], 2, s[82:83]
	v_mul_f32_e32 v2, v2, v177
.LBB0_98:
	ds_write_b32 v15, v2 offset:7128
	s_and_b64 vcc, exec, s[4:5]
	s_waitcnt vmcnt(35)
	v_cndmask_b32_e64 v2, 0, v19, s[6:7]
	s_cbranch_vccnz .LBB0_100
	v_lshl_add_u64 v[20:21], v[10:11], 2, s[82:83]
	v_mul_f32_e32 v2, v2, v178
.LBB0_100:
	ds_write_b32 v15, v2 offset:7392
	s_and_b64 vcc, exec, s[4:5]
	s_waitcnt vmcnt(34)
	v_cndmask_b32_e64 v2, 0, v18, s[6:7]
	s_cbranch_vccnz .LBB0_102
	v_lshl_add_u64 v[18:19], v[10:11], 2, s[82:83]
	v_mul_f32_e32 v2, v2, v179
.LBB0_102:
	ds_write_b32 v15, v2 offset:7656
	s_and_b64 vcc, exec, s[4:5]
	s_waitcnt vmcnt(33)
	v_cndmask_b32_e64 v2, 0, v17, s[6:7]
	s_cbranch_vccnz .LBB0_104
	v_lshl_add_u64 v[18:19], v[10:11], 2, s[82:83]
	v_mul_f32_e32 v2, v2, v180
.LBB0_104:
	ds_write_b32 v15, v2 offset:7920
	s_and_b64 vcc, exec, s[4:5]
	s_waitcnt vmcnt(32)
	v_cndmask_b32_e64 v2, 0, v16, s[6:7]
	s_cbranch_vccnz .LBB0_106
	v_lshl_add_u64 v[10:11], v[10:11], 2, s[82:83]
	v_mul_f32_e32 v2, v2, v181

; #define LAS __attribute__((address_space(3)))
; __device__ __forceinline__ void tr_load(const TrItem& t, float (&v)[32], int lane) {
;     const int n = lane & 31, kh = lane >> 5; const float* wp = t.W + (size_t)(t.k0 + kh) * t.ldw + t.n0 + (n < t.nvalid ? n : 0);
; #pragma unroll
;     for (int i = 0; i < 32; ++i) v[i] = wp[(size_t)(2 * i) * t.ldw];
; }
; __device__ __forceinline__ void tr_finish(const TrItem& t, const float (&v)[32], LAS float* scr, int lane) {
;     const int n = lane & 31, kh = lane >> 5;
; #pragma unroll
;     for (int i = 0; i < 32; ++i) { float x = n < t.nvalid ? v[i] : 0.f; if (t.g) x *= t.g[t.k0 + 2 * i + kh]; scr[(2 * i + kh) * 33 + n] = x; }
; __device__ __forceinline__ void tr_run(const P0Args& a, int grp, int nitems, int wk, int nwk, LAS float* scr, int lane) {
;     ...
;             const int i2 = it + 2 * nwk; const bool h2 = i2 < nitems; tr_decode(a, tr_group_item(grp, h2 ? i2 : it), A); tr_load(A, va, lane);
;             __builtin_amdgcn_sched_barrier(0);
;             if (h1) tr_finish(B, vb, scr, lane);
.LBB0_133:
	v_add_u32_e32 v2, s28, v1
	v_ashrrev_i32_e32 v7, 31, v2
	v_mul_lo_u32 v7, s74, v7
	v_mul_lo_u32 v16, s75, v2
	v_mad_u64_u32 v[10:11], s[0:1], s74, v2, 0
	v_add3_u32 v11, v11, v7, v16
	v_cmp_gt_u32_e32 vcc, s29, v0
	v_lshl_add_u64 v[10:11], v[10:11], 2, s[4:5]
	s_ashr_i32 s21, s20, 31
	v_cndmask_b32_e32 v2, 0, v0, vcc
	v_lshl_add_u64 v[10:11], s[20:21], 2, v[10:11]
	v_lshlrev_b32_e32 v2, 2, v2
	v_lshl_add_u64 v[10:11], v[10:11], 0, v[2:3]
	s_lshl_b64 s[0:1], s[74:75], 3
	v_lshl_add_u64 v[16:17], v[10:11], 0, s[0:1]
	v_lshl_add_u64 v[18:19], v[16:17], 0, s[0:1]
	v_lshl_add_u64 v[20:21], v[18:19], 0, s[0:1]
	v_lshl_add_u64 v[22:23], v[20:21], 0, s[0:1]
	v_lshl_add_u64 v[24:25], v[22:23], 0, s[0:1]
	v_lshl_add_u64 v[26:27], v[24:25], 0, s[0:1]
	v_lshl_add_u64 v[28:29], v[26:27], 0, s[0:1]
	global_load_dword v11, v[10:11], off
	s_nop 0
	global_load_dword v55, v[16:17], off
	global_load_dword v52, v[18:19], off
	global_load_dword v50, v[20:21], off
	global_load_dword v48, v[22:23], off
	global_load_dword v45, v[24:25], off
	global_load_dword v41, v[26:27], off
	global_load_dword v38, v[28:29], off
	v_lshl_add_u64 v[16:17], v[28:29], 0, s[0:1]
	global_load_dword v46, v[16:17], off
	v_lshl_add_u64 v[16:17], v[16:17], 0, s[0:1]
	global_load_dword v43, v[16:17], off
	v_lshl_add_u64 v[16:17], v[16:17], 0, s[0:1]
	global_load_dword v40, v[16:17], off
	v_lshl_add_u64 v[16:17], v[16:17], 0, s[0:1]
	global_load_dword v36, v[16:17], off
	v_lshl_add_u64 v[16:17], v[16:17], 0, s[0:1]
	global_load_dword v35, v[16:17], off
	v_lshl_add_u64 v[16:17], v[16:17], 0, s[0:1]
	global_load_dword v33, v[16:17], off
	v_lshl_add_u64 v[16:17], v[16:17], 0, s[0:1]
	global_load_dword v31, v[16:17], off
	v_lshl_add_u64 v[16:17], v[16:17], 0, s[0:1]
	global_load_dword v29, v[16:17], off
	v_lshl_add_u64 v[16:17], v[16:17], 0, s[0:1]
	global_load_dword v34, v[16:17], off
	v_lshl_add_u64 v[16:17], v[16:17], 0, s[0:1]
	global_load_dword v32, v[16:17], off
	v_lshl_add_u64 v[16:17], v[16:17], 0, s[0:1]
	global_load_dword v30, v[16:17], off
	v_lshl_add_u64 v[16:17], v[16:17], 0, s[0:1]
	global_load_dword v28, v[16:17], off
	v_lshl_add_u64 v[16:17], v[16:17], 0, s[0:1]
	global_load_dword v27, v[16:17], off
	v_lshl_add_u64 v[16:17], v[16:17], 0, s[0:1]
	global_load_dword v25, v[16:17], off
	v_lshl_add_u64 v[16:17], v[16:17], 0, s[0:1]
	global_load_dword v23, v[16:17], off
	v_lshl_add_u64 v[16:17], v[16:17], 0, s[0:1]
	global_load_dword v21, v[16:17], off
	v_lshl_add_u64 v[16:17], v[16:17], 0, s[0:1]
	global_load_dword v26, v[16:17], off
	v_lshl_add_u64 v[16:17], v[16:17], 0, s[0:1]
	global_load_dword v24, v[16:17], off
	v_lshl_add_u64 v[16:17], v[16:17], 0, s[0:1]
	global_load_dword v22, v[16:17], off
	v_lshl_add_u64 v[16:17], v[16:17], 0, s[0:1]
	global_load_dword v20, v[16:17], off
	v_lshl_add_u64 v[16:17], v[16:17], 0, s[0:1]
	global_load_dword v19, v[16:17], off
	v_lshl_add_u64 v[16:17], v[16:17], 0, s[0:1]
	v_lshl_add_u64 v[80:81], v[16:17], 0, s[0:1]
	global_load_dword v18, v[16:17], off
	s_nop 0
	global_load_dword v17, v[80:81], off
	v_lshl_add_u64 v[80:81], v[80:81], 0, s[0:1]
	global_load_dword v16, v[80:81], off
	s_andn2_b64 vcc, exec, s[94:95]
	s_cbranch_vccnz .LBB0_14
	s_cmp_lg_u64 s[96:97], 0
	s_cselect_b64 s[0:1], -1, 0
	s_cmp_eq_u64 s[96:97], 0
	s_waitcnt vmcnt(62)
	v_cndmask_b32_e64 v2, 0, v78, s[90:91]
	v_lshl_add_u64 v[8:9], v[8:9], 2, s[96:97]
	s_cbranch_scc1 .LBB0_136
	global_load_dword v150, v[8:9], off
	global_load_dword v151, v[8:9], off offset:8
	global_load_dword v152, v[8:9], off offset:16
	global_load_dword v153, v[8:9], off offset:24
	global_load_dword v154, v[8:9], off offset:32
	global_load_dword v155, v[8:9], off offset:40
	global_load_dword v156, v[8:9], off offset:48
	global_load_dword v157, v[8:9], off offset:56
	global_load_dword v158, v[8:9], off offset:64
	global_load_dword v159, v[8:9], off offset:72
	global_load_dword v160, v[8:9], off offset:80
	global_load_dword v161, v[8:9], off offset:88
	global_load_dword v162, v[8:9], off offset:96
	global_load_dword v163, v[8:9], off offset:104
	global_load_dword v164, v[8:9], off offset:112
	global_load_dword v165, v[8:9], off offset:120
	global_load_dword v166, v[8:9], off offset:128
	global_load_dword v167, v[8:9], off offset:136
	global_load_dword v168, v[8:9], off offset:144
	global_load_dword v169, v[8:9], off offset:152
	global_load_dword v170, v[8:9], off offset:160
	global_load_dword v171, v[8:9], off offset:168
	global_load_dword v172, v[8:9], off offset:176
	global_load_dword v173, v[8:9], off offset:184
	global_load_dword v174, v[8:9], off offset:192
	global_load_dword v175, v[8:9], off offset:200
	global_load_dword v176, v[8:9], off offset:208
	global_load_dword v177, v[8:9], off offset:216
	global_load_dword v178, v[8:9], off offset:224
	global_load_dword v179, v[8:9], off offset:232
	global_load_dword v180, v[8:9], off offset:240
	global_load_dword v181, v[8:9], off offset:248
	s_waitcnt vmcnt(0)
	v_mul_f32_e32 v2, v2, v150
.LBB0_136:
	ds_write_b32 v15, v2
	v_cndmask_b32_e64 v2, 0, 1, s[0:1]
	v_cmp_ne_u32_e64 s[4:5], 1, v2
	s_andn2_b64 vcc, exec, s[0:1]
	v_cndmask_b32_e64 v2, 0, v77, s[90:91]
	s_cbranch_vccnz .LBB0_138
	v_mul_f32_e32 v2, v2, v151
.LBB0_138:
	ds_write_b32 v15, v2 offset:264
	s_and_b64 vcc, exec, s[4:5]
	v_cndmask_b32_e64 v2, 0, v76, s[90:91]
	s_cbranch_vccnz .LBB0_140
	v_mul_f32_e32 v2, v2, v152
; #define LAS __attribute__((address_space(3)))
; #define LDS_WAIT() asm volatile("s_waitcnt lgkmcnt(0)" ::: "memory")
; __device__ __forceinline__ void tr_finish(const TrItem& t, const float (&v)[32], LAS float* scr, int lane) {
;     const int n = lane & 31, kh = lane >> 5;
; #pragma unroll
;     for (int i = 0; i < 32; ++i) { float x = n < t.nvalid ? v[i] : 0.f; if (t.g) x *= t.g[t.k0 + 2 * i + kh]; scr[(2 * i + kh) * 33 + n] = x; }
;     LDS_WAIT(); asm volatile("" ::: "memory");
.LBB0_140:
	ds_write_b32 v15, v2 offset:528
	s_and_b64 vcc, exec, s[4:5]
	v_cndmask_b32_e64 v2, 0, v75, s[90:91]
	s_cbranch_vccnz .LBB0_142
	v_mul_f32_e32 v2, v2, v153
.LBB0_142:
	ds_write_b32 v15, v2 offset:792
	s_and_b64 vcc, exec, s[4:5]
	v_cndmask_b32_e64 v2, 0, v74, s[90:91]
	s_cbranch_vccnz .LBB0_144
	v_mul_f32_e32 v2, v2, v154
.LBB0_144:
	ds_write_b32 v15, v2 offset:1056
	s_and_b64 vcc, exec, s[4:5]
	v_cndmask_b32_e64 v2, 0, v73, s[90:91]
	s_cbranch_vccnz .LBB0_146
	v_mul_f32_e32 v2, v2, v155
.LBB0_146:
	ds_write_b32 v15, v2 offset:1320
	s_and_b64 vcc, exec, s[4:5]
	s_waitcnt vmcnt(61)
	v_cndmask_b32_e64 v2, 0, v72, s[90:91]
	s_cbranch_vccnz .LBB0_148
	v_mul_f32_e32 v2, v2, v156
.LBB0_148:
	ds_write_b32 v15, v2 offset:1584
	s_and_b64 vcc, exec, s[4:5]
	s_waitcnt vmcnt(60)
	v_cndmask_b32_e64 v2, 0, v71, s[90:91]
	s_cbranch_vccnz .LBB0_150
	v_mul_f32_e32 v2, v2, v157
.LBB0_150:
	ds_write_b32 v15, v2 offset:1848
	s_and_b64 vcc, exec, s[4:5]
	s_waitcnt vmcnt(59)
	v_cndmask_b32_e64 v2, 0, v70, s[90:91]
	s_cbranch_vccnz .LBB0_152
	v_mul_f32_e32 v2, v2, v158
.LBB0_152:
	ds_write_b32 v15, v2 offset:2112
	s_and_b64 vcc, exec, s[4:5]
	s_waitcnt vmcnt(58)
	v_cndmask_b32_e64 v2, 0, v69, s[90:91]
	s_cbranch_vccnz .LBB0_154
	v_mul_f32_e32 v2, v2, v159
.LBB0_154:
	ds_write_b32 v15, v2 offset:2376
	s_and_b64 vcc, exec, s[4:5]
	s_waitcnt vmcnt(57)
	v_cndmask_b32_e64 v2, 0, v68, s[90:91]
	s_cbranch_vccnz .LBB0_156
	v_mul_f32_e32 v2, v2, v160
.LBB0_156:
	ds_write_b32 v15, v2 offset:2640
	s_and_b64 vcc, exec, s[4:5]
	s_waitcnt vmcnt(56)
	v_cndmask_b32_e64 v2, 0, v67, s[90:91]
	s_cbranch_vccnz .LBB0_158
	v_mul_f32_e32 v2, v2, v161
.LBB0_158:
	ds_write_b32 v15, v2 offset:2904
	s_and_b64 vcc, exec, s[4:5]
	s_waitcnt vmcnt(55)
	v_cndmask_b32_e64 v2, 0, v66, s[90:91]
	s_cbranch_vccnz .LBB0_160
	v_mul_f32_e32 v2, v2, v162
.LBB0_160:
	ds_write_b32 v15, v2 offset:3168
	s_and_b64 vcc, exec, s[4:5]
	s_waitcnt vmcnt(54)
	v_cndmask_b32_e64 v2, 0, v65, s[90:91]
	s_cbranch_vccnz .LBB0_162
	v_mul_f32_e32 v2, v2, v163
.LBB0_162:
	ds_write_b32 v15, v2 offset:3432
	s_and_b64 vcc, exec, s[4:5]
	s_waitcnt vmcnt(53)
	v_cndmask_b32_e64 v2, 0, v64, s[90:91]
	s_cbranch_vccnz .LBB0_164
	v_mul_f32_e32 v2, v2, v164
.LBB0_164:
	ds_write_b32 v15, v2 offset:3696
	s_and_b64 vcc, exec, s[4:5]
	s_waitcnt vmcnt(52)
	v_cndmask_b32_e64 v2, 0, v63, s[90:91]
	s_cbranch_vccnz .LBB0_166
	v_mul_f32_e32 v2, v2, v165
.LBB0_166:
	ds_write_b32 v15, v2 offset:3960
	s_and_b64 vcc, exec, s[4:5]
	s_waitcnt vmcnt(51)
	v_cndmask_b32_e64 v2, 0, v62, s[90:91]
	s_cbranch_vccnz .LBB0_168
	v_mul_f32_e32 v2, v2, v166
.LBB0_168:
	ds_write_b32 v15, v2 offset:4224
	s_and_b64 vcc, exec, s[4:5]
	s_waitcnt vmcnt(50)
	v_cndmask_b32_e64 v2, 0, v61, s[90:91]
	s_cbranch_vccnz .LBB0_170
	v_mul_f32_e32 v2, v2, v167
.LBB0_170:
	ds_write_b32 v15, v2 offset:4488
	s_and_b64 vcc, exec, s[4:5]
	s_waitcnt vmcnt(49)
	v_cndmask_b32_e64 v2, 0, v60, s[90:91]
	s_cbranch_vccnz .LBB0_172
	v_mul_f32_e32 v2, v2, v168
.LBB0_172:
	ds_write_b32 v15, v2 offset:4752
	s_and_b64 vcc, exec, s[4:5]
	s_waitcnt vmcnt(48)
	v_cndmask_b32_e64 v2, 0, v59, s[90:91]
	s_cbranch_vccnz .LBB0_174
	v_mul_f32_e32 v2, v2, v169
.LBB0_174:
	ds_write_b32 v15, v2 offset:5016
	s_and_b64 vcc, exec, s[4:5]
	s_waitcnt vmcnt(47)
	v_cndmask_b32_e64 v2, 0, v58, s[90:91]
	s_cbranch_vccnz .LBB0_176
	v_mul_f32_e32 v2, v2, v170
.LBB0_176:
	ds_write_b32 v15, v2 offset:5280
	s_and_b64 vcc, exec, s[4:5]
	s_waitcnt vmcnt(46)
	v_cndmask_b32_e64 v2, 0, v57, s[90:91]
	s_cbranch_vccnz .LBB0_178
	v_mul_f32_e32 v2, v2, v171
.LBB0_178:
	ds_write_b32 v15, v2 offset:5544
	s_and_b64 vcc, exec, s[4:5]
	s_waitcnt vmcnt(45)
	v_cndmask_b32_e64 v2, 0, v56, s[90:91]
	s_cbranch_vccnz .LBB0_180
	v_mul_f32_e32 v2, v2, v172
.LBB0_180:
	ds_write_b32 v15, v2 offset:5808
	s_and_b64 vcc, exec, s[4:5]
	s_waitcnt vmcnt(44)
	v_cndmask_b32_e64 v2, 0, v54, s[90:91]
	s_cbranch_vccnz .LBB0_182
	v_mul_f32_e32 v2, v2, v173
.LBB0_182:
	ds_write_b32 v15, v2 offset:6072
	s_and_b64 vcc, exec, s[4:5]
	s_waitcnt vmcnt(43)
	v_cndmask_b32_e64 v2, 0, v53, s[90:91]
	s_cbranch_vccnz .LBB0_184
	v_mul_f32_e32 v2, v2, v174
.LBB0_184:
	ds_write_b32 v15, v2 offset:6336
	s_and_b64 vcc, exec, s[4:5]
	s_waitcnt vmcnt(42)
	v_cndmask_b32_e64 v2, 0, v51, s[90:91]
	s_cbranch_vccnz .LBB0_186
	v_mul_f32_e32 v2, v2, v175
.LBB0_186:
	ds_write_b32 v15, v2 offset:6600
	s_and_b64 vcc, exec, s[4:5]
	s_waitcnt vmcnt(41)
	v_cndmask_b32_e64 v2, 0, v49, s[90:91]
	s_cbranch_vccnz .LBB0_188
	v_mul_f32_e32 v2, v2, v176
.LBB0_188:
	ds_write_b32 v15, v2 offset:6864
	s_and_b64 vcc, exec, s[4:5]
	s_waitcnt vmcnt(40)
	v_cndmask_b32_e64 v2, 0, v47, s[90:91]
	s_cbranch_vccnz .LBB0_190
	v_mul_f32_e32 v2, v2, v177
.LBB0_190:
	ds_write_b32 v15, v2 offset:7128
	s_and_b64 vcc, exec, s[4:5]
	s_waitcnt vmcnt(39)
	v_cndmask_b32_e64 v2, 0, v44, s[90:91]
	s_cbranch_vccnz .LBB0_192
	v_mul_f32_e32 v2, v2, v178
.LBB0_192:
	ds_write_b32 v15, v2 offset:7392
	s_and_b64 vcc, exec, s[4:5]
	s_waitcnt vmcnt(38)
	v_cndmask_b32_e64 v2, 0, v42, s[90:91]
	s_cbranch_vccnz .LBB0_194
	v_mul_f32_e32 v2, v2, v179
.LBB0_194:
	ds_write_b32 v15, v2 offset:7656
	s_and_b64 vcc, exec, s[4:5]
	s_waitcnt vmcnt(37)
	v_cndmask_b32_e64 v2, 0, v39, s[90:91]
	s_cbranch_vccnz .LBB0_196
	v_mul_f32_e32 v2, v2, v180
.LBB0_196:
	ds_write_b32 v15, v2 offset:7920
	s_and_b64 vcc, exec, s[4:5]
	s_waitcnt vmcnt(36)
	v_cndmask_b32_e64 v2, 0, v37, s[90:91]
	s_cbranch_vccnz .LBB0_13
	v_mul_f32_e32 v2, v2, v181
	s_branch .LBB0_13

; #define LAS __attribute__((address_space(3)))
; __device__ __forceinline__ void tr_load(const TrItem& t, float (&v)[32], int lane) {
;     const int n = lane & 31, kh = lane >> 5; const float* wp = t.W + (size_t)(t.k0 + kh) * t.ldw + t.n0 + (n < t.nvalid ? n : 0);
; #pragma unroll
;     for (int i = 0; i < 32; ++i) v[i] = wp[(size_t)(2 * i) * t.ldw];
; }
; __device__ __forceinline__ void tr_finish(const TrItem& t, const float (&v)[32], LAS float* scr, int lane) {
;     const int n = lane & 31, kh = lane >> 5;
; #pragma unroll
;     for (int i = 0; i < 32; ++i) { float x = n < t.nvalid ? v[i] : 0.f; if (t.g) x *= t.g[t.k0 + 2 * i + kh]; scr[(2 * i + kh) * 33 + n] = x; }
.LBB0_758:
	v_add_u32_e32 v6, s54, v1
	v_ashrrev_i32_e32 v7, 31, v6
	v_mul_lo_u32 v2, s76, v7
	v_mul_lo_u32 v5, s77, v6
	s_waitcnt vmcnt(45)
	v_mad_u64_u32 v[50:51], s[0:1], s76, v6, 0
	v_add3_u32 v51, v51, v2, v5
	v_lshl_add_u64 v[50:51], v[50:51], 2, s[4:5]
	s_ashr_i32 s7, s6, 31
	v_cndmask_b32_e64 v2, 0, v0, s[78:79]
	v_lshl_add_u64 v[50:51], s[6:7], 2, v[50:51]
	v_lshlrev_b32_e32 v2, 2, v2
	v_lshl_add_u64 v[50:51], v[50:51], 0, v[2:3]
	s_lshl_b64 s[0:1], s[76:77], 3
	global_load_dword v78, v[50:51], off
	v_lshl_add_u64 v[50:51], v[50:51], 0, s[0:1]
	global_load_dword v77, v[50:51], off
	v_lshl_add_u64 v[50:51], v[50:51], 0, s[0:1]
	global_load_dword v76, v[50:51], off
	v_lshl_add_u64 v[50:51], v[50:51], 0, s[0:1]
	global_load_dword v75, v[50:51], off
	v_lshl_add_u64 v[50:51], v[50:51], 0, s[0:1]
	global_load_dword v74, v[50:51], off
	v_lshl_add_u64 v[50:51], v[50:51], 0, s[0:1]
	global_load_dword v73, v[50:51], off
	v_lshl_add_u64 v[50:51], v[50:51], 0, s[0:1]
	global_load_dword v71, v[50:51], off
	v_lshl_add_u64 v[50:51], v[50:51], 0, s[0:1]
	global_load_dword v72, v[50:51], off
	v_lshl_add_u64 v[50:51], v[50:51], 0, s[0:1]
	global_load_dword v70, v[50:51], off
	v_lshl_add_u64 v[50:51], v[50:51], 0, s[0:1]
	global_load_dword v69, v[50:51], off
	v_lshl_add_u64 v[50:51], v[50:51], 0, s[0:1]
	global_load_dword v68, v[50:51], off
	v_lshl_add_u64 v[50:51], v[50:51], 0, s[0:1]
	global_load_dword v67, v[50:51], off
	v_lshl_add_u64 v[50:51], v[50:51], 0, s[0:1]
	global_load_dword v66, v[50:51], off
	v_lshl_add_u64 v[50:51], v[50:51], 0, s[0:1]
	global_load_dword v65, v[50:51], off
	v_lshl_add_u64 v[50:51], v[50:51], 0, s[0:1]
	global_load_dword v64, v[50:51], off
	v_lshl_add_u64 v[50:51], v[50:51], 0, s[0:1]
	global_load_dword v62, v[50:51], off
	v_lshl_add_u64 v[50:51], v[50:51], 0, s[0:1]
	global_load_dword v60, v[50:51], off
	v_lshl_add_u64 v[50:51], v[50:51], 0, s[0:1]
	global_load_dword v59, v[50:51], off
	v_lshl_add_u64 v[50:51], v[50:51], 0, s[0:1]
	global_load_dword v57, v[50:51], off
	v_lshl_add_u64 v[50:51], v[50:51], 0, s[0:1]
	global_load_dword v55, v[50:51], off
	v_lshl_add_u64 v[50:51], v[50:51], 0, s[0:1]
	v_lshl_add_u64 v[80:81], v[50:51], 0, s[0:1]
	global_load_dword v53, v[50:51], off
	s_nop 0
	global_load_dword v51, v[80:81], off
	v_lshl_add_u64 v[80:81], v[80:81], 0, s[0:1]
	global_load_dword v50, v[80:81], off
	v_lshl_add_u64 v[80:81], v[80:81], 0, s[0:1]
	global_load_dword v48, v[80:81], off
	v_lshl_add_u64 v[80:81], v[80:81], 0, s[0:1]
	global_load_dword v46, v[80:81], off
	v_lshl_add_u64 v[80:81], v[80:81], 0, s[0:1]
	global_load_dword v44, v[80:81], off
	v_lshl_add_u64 v[80:81], v[80:81], 0, s[0:1]
	global_load_dword v42, v[80:81], off
	v_lshl_add_u64 v[80:81], v[80:81], 0, s[0:1]
	global_load_dword v40, v[80:81], off
	v_lshl_add_u64 v[80:81], v[80:81], 0, s[0:1]
	global_load_dword v38, v[80:81], off
	v_lshl_add_u64 v[80:81], v[80:81], 0, s[0:1]
	global_load_dword v36, v[80:81], off
	v_lshl_add_u64 v[80:81], v[80:81], 0, s[0:1]
	global_load_dword v34, v[80:81], off
	v_lshl_add_u64 v[80:81], v[80:81], 0, s[0:1]
	global_load_dword v32, v[80:81], off
	s_cmp_lg_u64 s[46:47], 0
	v_add_u32_e32 v8, s8, v1
	v_cmp_gt_u32_e64 s[4:5], s9, v0
	s_cselect_b64 s[0:1], -1, 0
	s_cmp_eq_u64 s[46:47], 0
	s_waitcnt vmcnt(62)
	v_cndmask_b32_e64 v2, 0, v9, s[4:5]
	v_ashrrev_i32_e32 v9, 31, v8
	s_cbranch_scc1 .LBB0_760
	v_lshl_add_u64 v[80:81], v[8:9], 2, s[46:47]
	global_load_dword v150, v[80:81], off
	global_load_dword v151, v[80:81], off offset:8
	global_load_dword v152, v[80:81], off offset:16
	global_load_dword v153, v[80:81], off offset:24
	global_load_dword v154, v[80:81], off offset:32
	global_load_dword v155, v[80:81], off offset:40
	global_load_dword v156, v[80:81], off offset:48
	global_load_dword v157, v[80:81], off offset:56
	global_load_dword v158, v[80:81], off offset:64
	global_load_dword v159, v[80:81], off offset:72
	global_load_dword v160, v[80:81], off offset:80
	global_load_dword v161, v[80:81], off offset:88
	global_load_dword v162, v[80:81], off offset:96
	global_load_dword v163, v[80:81], off offset:104
	global_load_dword v164, v[80:81], off offset:112
	global_load_dword v165, v[80:81], off offset:120
	global_load_dword v166, v[80:81], off offset:128
	global_load_dword v167, v[80:81], off offset:136
	global_load_dword v168, v[80:81], off offset:144
	global_load_dword v169, v[80:81], off offset:152
	global_load_dword v170, v[80:81], off offset:160
	global_load_dword v171, v[80:81], off offset:168
	global_load_dword v172, v[80:81], off offset:176
	global_load_dword v173, v[80:81], off offset:184
	global_load_dword v174, v[80:81], off offset:192
	global_load_dword v175, v[80:81], off offset:200
	global_load_dword v176, v[80:81], off offset:208
	global_load_dword v177, v[80:81], off offset:216
	global_load_dword v178, v[80:81], off offset:224
	global_load_dword v179, v[80:81], off offset:232
	global_load_dword v180, v[80:81], off offset:240
	global_load_dword v181, v[80:81], off offset:248
	s_waitcnt vmcnt(0)
	v_mul_f32_e32 v2, v2, v150
.LBB0_760:
	ds_write_b32 v15, v2
	v_cndmask_b32_e64 v2, 0, 1, s[0:1]
	v_cmp_ne_u32_e64 s[6:7], 1, v2
	s_andn2_b64 vcc, exec, s[0:1]
	v_cndmask_b32_e64 v2, 0, v63, s[4:5]
	s_cbranch_vccnz .LBB0_762
	v_lshl_add_u64 v[80:81], v[8:9], 2, s[46:47]
	v_mul_f32_e32 v2, v2, v151
.LBB0_762:
	ds_write_b32 v15, v2 offset:264
	s_and_b64 vcc, exec, s[6:7]
	s_waitcnt vmcnt(61)
	v_cndmask_b32_e64 v2, 0, v61, s[4:5]
	s_cbranch_vccnz .LBB0_764
	v_lshl_add_u64 v[80:81], v[8:9], 2, s[46:47]
	v_mul_f32_e32 v2, v2, v152
; #define LAS __attribute__((address_space(3)))
; #define LDS_WAIT() asm volatile("s_waitcnt lgkmcnt(0)" ::: "memory")
; __device__ __forceinline__ void tr_finish(const TrItem& t, const float (&v)[32], LAS float* scr, int lane) {
;     const int n = lane & 31, kh = lane >> 5;
; #pragma unroll
;     for (int i = 0; i < 32; ++i) { float x = n < t.nvalid ? v[i] : 0.f; if (t.g) x *= t.g[t.k0 + 2 * i + kh]; scr[(2 * i + kh) * 33 + n] = x; }
;     LDS_WAIT(); asm volatile("" ::: "memory");
.LBB0_764:
	ds_write_b32 v15, v2 offset:528
	s_and_b64 vcc, exec, s[6:7]
	s_waitcnt vmcnt(60)
	v_cndmask_b32_e64 v2, 0, v58, s[4:5]
	s_cbranch_vccnz .LBB0_766
	v_lshl_add_u64 v[80:81], v[8:9], 2, s[46:47]
	v_mul_f32_e32 v2, v2, v153
.LBB0_766:
	ds_write_b32 v15, v2 offset:792
	s_and_b64 vcc, exec, s[6:7]
	s_waitcnt vmcnt(59)
	v_cndmask_b32_e64 v2, 0, v56, s[4:5]
	s_cbranch_vccnz .LBB0_768
	v_lshl_add_u64 v[80:81], v[8:9], 2, s[46:47]
	v_mul_f32_e32 v2, v2, v154
.LBB0_768:
	ds_write_b32 v15, v2 offset:1056
	s_and_b64 vcc, exec, s[6:7]
	s_waitcnt vmcnt(58)
	v_cndmask_b32_e64 v2, 0, v54, s[4:5]
	s_cbranch_vccnz .LBB0_770
	v_lshl_add_u64 v[80:81], v[8:9], 2, s[46:47]
	v_mul_f32_e32 v2, v2, v155
.LBB0_770:
	ds_write_b32 v15, v2 offset:1320
	s_and_b64 vcc, exec, s[6:7]
	s_waitcnt vmcnt(57)
	v_cndmask_b32_e64 v2, 0, v52, s[4:5]
	s_cbranch_vccnz .LBB0_772
	v_lshl_add_u64 v[80:81], v[8:9], 2, s[46:47]
	v_mul_f32_e32 v2, v2, v156
.LBB0_772:
	ds_write_b32 v15, v2 offset:1584
	s_and_b64 vcc, exec, s[6:7]
	s_waitcnt vmcnt(56)
	v_cndmask_b32_e64 v2, 0, v49, s[4:5]
	s_cbranch_vccnz .LBB0_774
	v_lshl_add_u64 v[80:81], v[8:9], 2, s[46:47]
	v_mul_f32_e32 v2, v2, v157
.LBB0_774:
	ds_write_b32 v15, v2 offset:1848
	s_and_b64 vcc, exec, s[6:7]
	s_waitcnt vmcnt(55)
	v_cndmask_b32_e64 v2, 0, v47, s[4:5]
	s_cbranch_vccnz .LBB0_776
	v_lshl_add_u64 v[80:81], v[8:9], 2, s[46:47]
	v_mul_f32_e32 v2, v2, v158
.LBB0_776:
	ds_write_b32 v15, v2 offset:2112
	s_and_b64 vcc, exec, s[6:7]
	s_waitcnt vmcnt(54)
	v_cndmask_b32_e64 v2, 0, v45, s[4:5]
	s_cbranch_vccnz .LBB0_778
	v_lshl_add_u64 v[80:81], v[8:9], 2, s[46:47]
	v_mul_f32_e32 v2, v2, v159
.LBB0_778:
	ds_write_b32 v15, v2 offset:2376
	s_and_b64 vcc, exec, s[6:7]
	s_waitcnt vmcnt(53)
	v_cndmask_b32_e64 v2, 0, v43, s[4:5]
	s_cbranch_vccnz .LBB0_780
	v_lshl_add_u64 v[80:81], v[8:9], 2, s[46:47]
	v_mul_f32_e32 v2, v2, v160
.LBB0_780:
	ds_write_b32 v15, v2 offset:2640
	s_and_b64 vcc, exec, s[6:7]
	s_waitcnt vmcnt(52)
	v_cndmask_b32_e64 v2, 0, v41, s[4:5]
	s_cbranch_vccnz .LBB0_782
	v_lshl_add_u64 v[80:81], v[8:9], 2, s[46:47]
	v_mul_f32_e32 v2, v2, v161
.LBB0_782:
	ds_write_b32 v15, v2 offset:2904
	s_and_b64 vcc, exec, s[6:7]
	s_waitcnt vmcnt(51)
	v_cndmask_b32_e64 v2, 0, v39, s[4:5]
	s_cbranch_vccnz .LBB0_784
	v_lshl_add_u64 v[80:81], v[8:9], 2, s[46:47]
	v_mul_f32_e32 v2, v2, v162
.LBB0_784:
	ds_write_b32 v15, v2 offset:3168
	s_and_b64 vcc, exec, s[6:7]
	s_waitcnt vmcnt(50)
	v_cndmask_b32_e64 v2, 0, v37, s[4:5]
	s_cbranch_vccnz .LBB0_786
	v_lshl_add_u64 v[80:81], v[8:9], 2, s[46:47]
	v_mul_f32_e32 v2, v2, v163
.LBB0_786:
	ds_write_b32 v15, v2 offset:3432
	s_and_b64 vcc, exec, s[6:7]
	s_waitcnt vmcnt(49)
	v_cndmask_b32_e64 v2, 0, v35, s[4:5]
	s_cbranch_vccnz .LBB0_788
	v_lshl_add_u64 v[80:81], v[8:9], 2, s[46:47]
	v_mul_f32_e32 v2, v2, v164
.LBB0_788:
	ds_write_b32 v15, v2 offset:3696
	s_and_b64 vcc, exec, s[6:7]
	s_waitcnt vmcnt(48)
	v_cndmask_b32_e64 v2, 0, v33, s[4:5]
	s_cbranch_vccnz .LBB0_790
	v_lshl_add_u64 v[80:81], v[8:9], 2, s[46:47]
	v_mul_f32_e32 v2, v2, v165
.LBB0_790:
	ds_write_b32 v15, v2 offset:3960
	s_and_b64 vcc, exec, s[6:7]
	s_waitcnt vmcnt(47)
	v_cndmask_b32_e64 v2, 0, v31, s[4:5]
	s_cbranch_vccnz .LBB0_792
	v_lshl_add_u64 v[80:81], v[8:9], 2, s[46:47]
	v_mul_f32_e32 v2, v2, v166
.LBB0_792:
	ds_write_b32 v15, v2 offset:4224
	s_and_b64 vcc, exec, s[6:7]
	s_waitcnt vmcnt(46)
	v_cndmask_b32_e64 v2, 0, v30, s[4:5]
	s_cbranch_vccnz .LBB0_794
	v_lshl_add_u64 v[30:31], v[8:9], 2, s[46:47]
	v_mul_f32_e32 v2, v2, v167
.LBB0_794:
	ds_write_b32 v15, v2 offset:4488
	s_and_b64 vcc, exec, s[6:7]
	s_waitcnt vmcnt(45)
	v_cndmask_b32_e64 v2, 0, v29, s[4:5]
	s_cbranch_vccnz .LBB0_796
	v_lshl_add_u64 v[30:31], v[8:9], 2, s[46:47]
	v_mul_f32_e32 v2, v2, v168
.LBB0_796:
	ds_write_b32 v15, v2 offset:4752
	s_and_b64 vcc, exec, s[6:7]
	s_waitcnt vmcnt(44)
	v_cndmask_b32_e64 v2, 0, v28, s[4:5]
	s_cbranch_vccnz .LBB0_798
	v_lshl_add_u64 v[28:29], v[8:9], 2, s[46:47]
	v_mul_f32_e32 v2, v2, v169
.LBB0_798:
	ds_write_b32 v15, v2 offset:5016
	s_and_b64 vcc, exec, s[6:7]
	s_waitcnt vmcnt(43)
	v_cndmask_b32_e64 v2, 0, v27, s[4:5]
	s_cbranch_vccnz .LBB0_800
	v_lshl_add_u64 v[28:29], v[8:9], 2, s[46:47]
	v_mul_f32_e32 v2, v2, v170
.LBB0_800:
	ds_write_b32 v15, v2 offset:5280
	s_and_b64 vcc, exec, s[6:7]
	s_waitcnt vmcnt(42)
	v_cndmask_b32_e64 v2, 0, v26, s[4:5]
	s_cbranch_vccnz .LBB0_802
	v_lshl_add_u64 v[26:27], v[8:9], 2, s[46:47]
	v_mul_f32_e32 v2, v2, v171
.LBB0_802:
	ds_write_b32 v15, v2 offset:5544
	s_and_b64 vcc, exec, s[6:7]
	s_waitcnt vmcnt(41)
	v_cndmask_b32_e64 v2, 0, v25, s[4:5]
	s_cbranch_vccnz .LBB0_804
	v_lshl_add_u64 v[26:27], v[8:9], 2, s[46:47]
	v_mul_f32_e32 v2, v2, v172
.LBB0_804:
	ds_write_b32 v15, v2 offset:5808
	s_and_b64 vcc, exec, s[6:7]
	s_waitcnt vmcnt(40)
	v_cndmask_b32_e64 v2, 0, v24, s[4:5]
	s_cbranch_vccnz .LBB0_806
	v_lshl_add_u64 v[24:25], v[8:9], 2, s[46:47]
	v_mul_f32_e32 v2, v2, v173
.LBB0_806:
	ds_write_b32 v15, v2 offset:6072
	s_and_b64 vcc, exec, s[6:7]
	s_waitcnt vmcnt(39)
	v_cndmask_b32_e64 v2, 0, v23, s[4:5]
	s_cbranch_vccnz .LBB0_808
	v_lshl_add_u64 v[24:25], v[8:9], 2, s[46:47]
	v_mul_f32_e32 v2, v2, v174
.LBB0_808:
	ds_write_b32 v15, v2 offset:6336
	s_and_b64 vcc, exec, s[6:7]
	s_waitcnt vmcnt(38)
	v_cndmask_b32_e64 v2, 0, v22, s[4:5]
	s_cbranch_vccnz .LBB0_810
	v_lshl_add_u64 v[22:23], v[8:9], 2, s[46:47]
	v_mul_f32_e32 v2, v2, v175
.LBB0_810:
	ds_write_b32 v15, v2 offset:6600
	s_and_b64 vcc, exec, s[6:7]
	s_waitcnt vmcnt(37)
	v_cndmask_b32_e64 v2, 0, v21, s[4:5]
	s_cbranch_vccnz .LBB0_812
	v_lshl_add_u64 v[22:23], v[8:9], 2, s[46:47]
	v_mul_f32_e32 v2, v2, v176
.LBB0_812:
	ds_write_b32 v15, v2 offset:6864
	s_and_b64 vcc, exec, s[6:7]
	s_waitcnt vmcnt(36)
	v_cndmask_b32_e64 v2, 0, v20, s[4:5]
	s_cbranch_vccnz .LBB0_814
	v_lshl_add_u64 v[20:21], v[8:9], 2, s[46:47]
	v_mul_f32_e32 v2, v2, v177
.LBB0_814:
	ds_write_b32 v15, v2 offset:7128
	s_and_b64 vcc, exec, s[6:7]
	s_waitcnt vmcnt(35)
	v_cndmask_b32_e64 v2, 0, v19, s[4:5]
	s_cbranch_vccnz .LBB0_816
	v_lshl_add_u64 v[20:21], v[8:9], 2, s[46:47]
	v_mul_f32_e32 v2, v2, v178
.LBB0_816:
	ds_write_b32 v15, v2 offset:7392
	s_and_b64 vcc, exec, s[6:7]
	s_waitcnt vmcnt(34)
	v_cndmask_b32_e64 v2, 0, v18, s[4:5]
	s_cbranch_vccnz .LBB0_818
	v_lshl_add_u64 v[18:19], v[8:9], 2, s[46:47]
	v_mul_f32_e32 v2, v2, v179
.LBB0_818:
	ds_write_b32 v15, v2 offset:7656
	s_and_b64 vcc, exec, s[6:7]
	s_waitcnt vmcnt(33)
	v_cndmask_b32_e64 v2, 0, v17, s[4:5]
	s_cbranch_vccnz .LBB0_820
	v_lshl_add_u64 v[18:19], v[8:9], 2, s[46:47]
	v_mul_f32_e32 v2, v2, v180
.LBB0_820:
	ds_write_b32 v15, v2 offset:7920
	s_and_b64 vcc, exec, s[6:7]
	s_waitcnt vmcnt(32)
	v_cndmask_b32_e64 v2, 0, v16, s[4:5]
	s_cbranch_vccnz .LBB0_822
	v_lshl_add_u64 v[8:9], v[8:9], 2, s[46:47]
	v_mul_f32_e32 v2, v2, v181

; #define LAS __attribute__((address_space(3)))
; __device__ __forceinline__ void tr_load(const TrItem& t, float (&v)[32], int lane) {
;     const int n = lane & 31, kh = lane >> 5; const float* wp = t.W + (size_t)(t.k0 + kh) * t.ldw + t.n0 + (n < t.nvalid ? n : 0);
; #pragma unroll
;     for (int i = 0; i < 32; ++i) v[i] = wp[(size_t)(2 * i) * t.ldw];
; }
; __device__ __forceinline__ void tr_finish(const TrItem& t, const float (&v)[32], LAS float* scr, int lane) {
;     const int n = lane & 31, kh = lane >> 5;
; #pragma unroll
;     for (int i = 0; i < 32; ++i) { float x = n < t.nvalid ? v[i] : 0.f; if (t.g) x *= t.g[t.k0 + 2 * i + kh]; scr[(2 * i + kh) * 33 + n] = x; }
; __device__ __forceinline__ void tr_run(const P0Args& a, int grp, int nitems, int wk, int nwk, LAS float* scr, int lane) {
;     ...
;             const int i2 = it + 2 * nwk; const bool h2 = i2 < nitems; tr_decode(a, tr_group_item(grp, h2 ? i2 : it), A); tr_load(A, va, lane);
;             __builtin_amdgcn_sched_barrier(0);
;             if (h1) tr_finish(B, vb, scr, lane);
.LBB0_848:
	v_add_u32_e32 v2, s8, v1
	v_ashrrev_i32_e32 v5, 31, v2
	v_mul_lo_u32 v5, s74, v5
	v_mul_lo_u32 v16, s75, v2
	v_mad_u64_u32 v[8:9], s[0:1], s74, v2, 0
	v_add3_u32 v9, v9, v5, v16
	v_cmp_gt_u32_e32 vcc, s9, v0
	v_lshl_add_u64 v[8:9], v[8:9], 2, s[4:5]
	s_ashr_i32 s7, s6, 31
	v_cndmask_b32_e32 v2, 0, v0, vcc
	v_lshl_add_u64 v[8:9], s[6:7], 2, v[8:9]
	v_lshlrev_b32_e32 v2, 2, v2
	v_lshl_add_u64 v[8:9], v[8:9], 0, v[2:3]
	s_lshl_b64 s[0:1], s[74:75], 3
	v_lshl_add_u64 v[16:17], v[8:9], 0, s[0:1]
	v_lshl_add_u64 v[18:19], v[16:17], 0, s[0:1]
	v_lshl_add_u64 v[20:21], v[18:19], 0, s[0:1]
	v_lshl_add_u64 v[22:23], v[20:21], 0, s[0:1]
	v_lshl_add_u64 v[24:25], v[22:23], 0, s[0:1]
	v_lshl_add_u64 v[26:27], v[24:25], 0, s[0:1]
	v_lshl_add_u64 v[28:29], v[26:27], 0, s[0:1]
	global_load_dword v9, v[8:9], off
	s_nop 0
	global_load_dword v63, v[16:17], off
	global_load_dword v61, v[18:19], off
	global_load_dword v58, v[20:21], off
	global_load_dword v56, v[22:23], off
	global_load_dword v54, v[24:25], off
	global_load_dword v52, v[26:27], off
	global_load_dword v49, v[28:29], off
	v_lshl_add_u64 v[16:17], v[28:29], 0, s[0:1]
	global_load_dword v47, v[16:17], off
	v_lshl_add_u64 v[16:17], v[16:17], 0, s[0:1]
	global_load_dword v45, v[16:17], off
	v_lshl_add_u64 v[16:17], v[16:17], 0, s[0:1]
	global_load_dword v43, v[16:17], off
	v_lshl_add_u64 v[16:17], v[16:17], 0, s[0:1]
	global_load_dword v41, v[16:17], off
	v_lshl_add_u64 v[16:17], v[16:17], 0, s[0:1]
	global_load_dword v39, v[16:17], off
	v_lshl_add_u64 v[16:17], v[16:17], 0, s[0:1]
	global_load_dword v37, v[16:17], off
	v_lshl_add_u64 v[16:17], v[16:17], 0, s[0:1]
	global_load_dword v35, v[16:17], off
	v_lshl_add_u64 v[16:17], v[16:17], 0, s[0:1]
	global_load_dword v33, v[16:17], off
	v_lshl_add_u64 v[16:17], v[16:17], 0, s[0:1]
	global_load_dword v31, v[16:17], off
	v_lshl_add_u64 v[16:17], v[16:17], 0, s[0:1]
	global_load_dword v30, v[16:17], off
	v_lshl_add_u64 v[16:17], v[16:17], 0, s[0:1]
	global_load_dword v29, v[16:17], off
	v_lshl_add_u64 v[16:17], v[16:17], 0, s[0:1]
	global_load_dword v28, v[16:17], off
	v_lshl_add_u64 v[16:17], v[16:17], 0, s[0:1]
	global_load_dword v27, v[16:17], off
	v_lshl_add_u64 v[16:17], v[16:17], 0, s[0:1]
	global_load_dword v26, v[16:17], off
	v_lshl_add_u64 v[16:17], v[16:17], 0, s[0:1]
	global_load_dword v25, v[16:17], off
	v_lshl_add_u64 v[16:17], v[16:17], 0, s[0:1]
	global_load_dword v24, v[16:17], off
	v_lshl_add_u64 v[16:17], v[16:17], 0, s[0:1]
	global_load_dword v23, v[16:17], off
	v_lshl_add_u64 v[16:17], v[16:17], 0, s[0:1]
	global_load_dword v22, v[16:17], off
	v_lshl_add_u64 v[16:17], v[16:17], 0, s[0:1]
	global_load_dword v21, v[16:17], off
	v_lshl_add_u64 v[16:17], v[16:17], 0, s[0:1]
	global_load_dword v20, v[16:17], off
	v_lshl_add_u64 v[16:17], v[16:17], 0, s[0:1]
	global_load_dword v19, v[16:17], off
	v_lshl_add_u64 v[16:17], v[16:17], 0, s[0:1]
	v_lshl_add_u64 v[80:81], v[16:17], 0, s[0:1]
	global_load_dword v18, v[16:17], off
	s_nop 0
	global_load_dword v17, v[80:81], off
	v_lshl_add_u64 v[80:81], v[80:81], 0, s[0:1]
	global_load_dword v16, v[80:81], off
	s_andn2_b64 vcc, exec, s[82:83]
	s_cbranch_vccnz .LBB0_731
	s_cmp_lg_u64 s[84:85], 0
	s_cselect_b64 s[0:1], -1, 0
	s_cmp_eq_u64 s[84:85], 0
	s_waitcnt vmcnt(62)
	v_cndmask_b32_e64 v2, 0, v78, s[78:79]
	v_lshl_add_u64 v[6:7], v[6:7], 2, s[84:85]
	s_cbranch_scc1 .LBB0_851
	global_load_dword v150, v[6:7], off
	global_load_dword v151, v[6:7], off offset:8
	global_load_dword v152, v[6:7], off offset:16
	global_load_dword v153, v[6:7], off offset:24
	global_load_dword v154, v[6:7], off offset:32
	global_load_dword v155, v[6:7], off offset:40
	global_load_dword v156, v[6:7], off offset:48
	global_load_dword v157, v[6:7], off offset:56
	global_load_dword v158, v[6:7], off offset:64
	global_load_dword v159, v[6:7], off offset:72
	global_load_dword v160, v[6:7], off offset:80
	global_load_dword v161, v[6:7], off offset:88
	global_load_dword v162, v[6:7], off offset:96
	global_load_dword v163, v[6:7], off offset:104
	global_load_dword v164, v[6:7], off offset:112
	global_load_dword v165, v[6:7], off offset:120
	global_load_dword v166, v[6:7], off offset:128
	global_load_dword v167, v[6:7], off offset:136
	global_load_dword v168, v[6:7], off offset:144
	global_load_dword v169, v[6:7], off offset:152
	global_load_dword v170, v[6:7], off offset:160
	global_load_dword v171, v[6:7], off offset:168
	global_load_dword v172, v[6:7], off offset:176
	global_load_dword v173, v[6:7], off offset:184
	global_load_dword v174, v[6:7], off offset:192
	global_load_dword v175, v[6:7], off offset:200
	global_load_dword v176, v[6:7], off offset:208
	global_load_dword v177, v[6:7], off offset:216
	global_load_dword v178, v[6:7], off offset:224
	global_load_dword v179, v[6:7], off offset:232
	global_load_dword v180, v[6:7], off offset:240
	global_load_dword v181, v[6:7], off offset:248
	s_waitcnt vmcnt(0)
	v_mul_f32_e32 v2, v2, v150
.LBB0_851:
	ds_write_b32 v15, v2
	v_cndmask_b32_e64 v2, 0, 1, s[0:1]
	v_cmp_ne_u32_e64 s[4:5], 1, v2
	s_andn2_b64 vcc, exec, s[0:1]
	v_cndmask_b32_e64 v2, 0, v77, s[78:79]
	s_cbranch_vccnz .LBB0_853
	v_mul_f32_e32 v2, v2, v151
.LBB0_853:
	ds_write_b32 v15, v2 offset:264
	s_and_b64 vcc, exec, s[4:5]
	v_cndmask_b32_e64 v2, 0, v76, s[78:79]
	s_cbranch_vccnz .LBB0_855
	v_mul_f32_e32 v2, v2, v152
; #define LAS __attribute__((address_space(3)))
; #define LDS_WAIT() asm volatile("s_waitcnt lgkmcnt(0)" ::: "memory")
; __device__ __forceinline__ void tr_finish(const TrItem& t, const float (&v)[32], LAS float* scr, int lane) {
;     const int n = lane & 31, kh = lane >> 5;
; #pragma unroll
;     for (int i = 0; i < 32; ++i) { float x = n < t.nvalid ? v[i] : 0.f; if (t.g) x *= t.g[t.k0 + 2 * i + kh]; scr[(2 * i + kh) * 33 + n] = x; }
;     LDS_WAIT(); asm volatile("" ::: "memory");
.LBB0_855:
	ds_write_b32 v15, v2 offset:528
	s_and_b64 vcc, exec, s[4:5]
	v_cndmask_b32_e64 v2, 0, v75, s[78:79]
	s_cbranch_vccnz .LBB0_857
	v_mul_f32_e32 v2, v2, v153
.LBB0_857:
	ds_write_b32 v15, v2 offset:792
	s_and_b64 vcc, exec, s[4:5]
	v_cndmask_b32_e64 v2, 0, v74, s[78:79]
	s_cbranch_vccnz .LBB0_859
	v_mul_f32_e32 v2, v2, v154
.LBB0_859:
	ds_write_b32 v15, v2 offset:1056
	s_and_b64 vcc, exec, s[4:5]
	v_cndmask_b32_e64 v2, 0, v73, s[78:79]
	s_cbranch_vccnz .LBB0_861
	v_mul_f32_e32 v2, v2, v155
.LBB0_861:
	ds_write_b32 v15, v2 offset:1320
	s_and_b64 vcc, exec, s[4:5]
	s_waitcnt vmcnt(61)
	v_cndmask_b32_e64 v2, 0, v71, s[78:79]
	s_cbranch_vccnz .LBB0_863
	v_mul_f32_e32 v2, v2, v156
.LBB0_863:
	ds_write_b32 v15, v2 offset:1584
	s_and_b64 vcc, exec, s[4:5]
	s_waitcnt vmcnt(60)
	v_cndmask_b32_e64 v2, 0, v72, s[78:79]
	s_cbranch_vccnz .LBB0_865
	v_mul_f32_e32 v2, v2, v157
.LBB0_865:
	ds_write_b32 v15, v2 offset:1848
	s_and_b64 vcc, exec, s[4:5]
	s_waitcnt vmcnt(59)
	v_cndmask_b32_e64 v2, 0, v70, s[78:79]
	s_cbranch_vccnz .LBB0_867
	v_mul_f32_e32 v2, v2, v158
.LBB0_867:
	ds_write_b32 v15, v2 offset:2112
	s_and_b64 vcc, exec, s[4:5]
	s_waitcnt vmcnt(58)
	v_cndmask_b32_e64 v2, 0, v69, s[78:79]
	s_cbranch_vccnz .LBB0_869
	v_mul_f32_e32 v2, v2, v159
.LBB0_869:
	ds_write_b32 v15, v2 offset:2376
	s_and_b64 vcc, exec, s[4:5]
	s_waitcnt vmcnt(57)
	v_cndmask_b32_e64 v2, 0, v68, s[78:79]
	s_cbranch_vccnz .LBB0_871
	v_mul_f32_e32 v2, v2, v160
.LBB0_871:
	ds_write_b32 v15, v2 offset:2640
	s_and_b64 vcc, exec, s[4:5]
	s_waitcnt vmcnt(56)
	v_cndmask_b32_e64 v2, 0, v67, s[78:79]
	s_cbranch_vccnz .LBB0_873
	v_mul_f32_e32 v2, v2, v161
.LBB0_873:
	ds_write_b32 v15, v2 offset:2904
	s_and_b64 vcc, exec, s[4:5]
	s_waitcnt vmcnt(55)
	v_cndmask_b32_e64 v2, 0, v66, s[78:79]
	s_cbranch_vccnz .LBB0_875
	v_mul_f32_e32 v2, v2, v162
.LBB0_875:
	ds_write_b32 v15, v2 offset:3168
	s_and_b64 vcc, exec, s[4:5]
	s_waitcnt vmcnt(54)
	v_cndmask_b32_e64 v2, 0, v65, s[78:79]
	s_cbranch_vccnz .LBB0_877
	v_mul_f32_e32 v2, v2, v163
.LBB0_877:
	ds_write_b32 v15, v2 offset:3432
	s_and_b64 vcc, exec, s[4:5]
	s_waitcnt vmcnt(53)
	v_cndmask_b32_e64 v2, 0, v64, s[78:79]
	s_cbranch_vccnz .LBB0_879
	v_mul_f32_e32 v2, v2, v164
.LBB0_879:
	ds_write_b32 v15, v2 offset:3696
	s_and_b64 vcc, exec, s[4:5]
	s_waitcnt vmcnt(52)
	v_cndmask_b32_e64 v2, 0, v62, s[78:79]
	s_cbranch_vccnz .LBB0_881
	v_mul_f32_e32 v2, v2, v165
.LBB0_881:
	ds_write_b32 v15, v2 offset:3960
	s_and_b64 vcc, exec, s[4:5]
	s_waitcnt vmcnt(51)
	v_cndmask_b32_e64 v2, 0, v60, s[78:79]
	s_cbranch_vccnz .LBB0_883
	v_mul_f32_e32 v2, v2, v166
.LBB0_883:
	ds_write_b32 v15, v2 offset:4224
	s_and_b64 vcc, exec, s[4:5]
	s_waitcnt vmcnt(50)
	v_cndmask_b32_e64 v2, 0, v59, s[78:79]
	s_cbranch_vccnz .LBB0_885
	v_mul_f32_e32 v2, v2, v167
.LBB0_885:
	ds_write_b32 v15, v2 offset:4488
	s_and_b64 vcc, exec, s[4:5]
	s_waitcnt vmcnt(49)
	v_cndmask_b32_e64 v2, 0, v57, s[78:79]
	s_cbranch_vccnz .LBB0_887
	v_mul_f32_e32 v2, v2, v168
.LBB0_887:
	ds_write_b32 v15, v2 offset:4752
	s_and_b64 vcc, exec, s[4:5]
	s_waitcnt vmcnt(48)
	v_cndmask_b32_e64 v2, 0, v55, s[78:79]
	s_cbranch_vccnz .LBB0_889
	v_mul_f32_e32 v2, v2, v169
.LBB0_889:
	ds_write_b32 v15, v2 offset:5016
	s_and_b64 vcc, exec, s[4:5]
	s_waitcnt vmcnt(47)
	v_cndmask_b32_e64 v2, 0, v53, s[78:79]
	s_cbranch_vccnz .LBB0_891
	v_mul_f32_e32 v2, v2, v170
.LBB0_891:
	ds_write_b32 v15, v2 offset:5280
	s_and_b64 vcc, exec, s[4:5]
	s_waitcnt vmcnt(46)
	v_cndmask_b32_e64 v2, 0, v51, s[78:79]
	s_cbranch_vccnz .LBB0_893
	v_mul_f32_e32 v2, v2, v171
.LBB0_893:
	ds_write_b32 v15, v2 offset:5544
	s_and_b64 vcc, exec, s[4:5]
	s_waitcnt vmcnt(45)
	v_cndmask_b32_e64 v2, 0, v50, s[78:79]
	s_cbranch_vccnz .LBB0_895
	v_mul_f32_e32 v2, v2, v172
.LBB0_895:
	ds_write_b32 v15, v2 offset:5808
	s_and_b64 vcc, exec, s[4:5]
	s_waitcnt vmcnt(44)
	v_cndmask_b32_e64 v2, 0, v48, s[78:79]
	s_cbranch_vccnz .LBB0_897
	v_mul_f32_e32 v2, v2, v173
.LBB0_897:
	ds_write_b32 v15, v2 offset:6072
	s_and_b64 vcc, exec, s[4:5]
	s_waitcnt vmcnt(43)
	v_cndmask_b32_e64 v2, 0, v46, s[78:79]
	s_cbranch_vccnz .LBB0_899
	v_mul_f32_e32 v2, v2, v174
.LBB0_899:
	ds_write_b32 v15, v2 offset:6336
	s_and_b64 vcc, exec, s[4:5]
	s_waitcnt vmcnt(42)
	v_cndmask_b32_e64 v2, 0, v44, s[78:79]
	s_cbranch_vccnz .LBB0_901
	v_mul_f32_e32 v2, v2, v175
.LBB0_901:
	ds_write_b32 v15, v2 offset:6600
	s_and_b64 vcc, exec, s[4:5]
	s_waitcnt vmcnt(41)
	v_cndmask_b32_e64 v2, 0, v42, s[78:79]
	s_cbranch_vccnz .LBB0_903
	v_mul_f32_e32 v2, v2, v176
.LBB0_903:
	ds_write_b32 v15, v2 offset:6864
	s_and_b64 vcc, exec, s[4:5]
	s_waitcnt vmcnt(40)
	v_cndmask_b32_e64 v2, 0, v40, s[78:79]
	s_cbranch_vccnz .LBB0_905
	v_mul_f32_e32 v2, v2, v177
.LBB0_905:
	ds_write_b32 v15, v2 offset:7128
	s_and_b64 vcc, exec, s[4:5]
	s_waitcnt vmcnt(39)
	v_cndmask_b32_e64 v2, 0, v38, s[78:79]
	s_cbranch_vccnz .LBB0_907
	v_mul_f32_e32 v2, v2, v178
.LBB0_907:
	ds_write_b32 v15, v2 offset:7392
	s_and_b64 vcc, exec, s[4:5]
	s_waitcnt vmcnt(38)
	v_cndmask_b32_e64 v2, 0, v36, s[78:79]
	s_cbranch_vccnz .LBB0_909
	v_mul_f32_e32 v2, v2, v179
.LBB0_909:
	ds_write_b32 v15, v2 offset:7656
	s_and_b64 vcc, exec, s[4:5]
	s_waitcnt vmcnt(37)
	v_cndmask_b32_e64 v2, 0, v34, s[78:79]
	s_cbranch_vccnz .LBB0_911
	v_mul_f32_e32 v2, v2, v180
.LBB0_911:
	ds_write_b32 v15, v2 offset:7920
	s_and_b64 vcc, exec, s[4:5]
	s_waitcnt vmcnt(36)
	v_cndmask_b32_e64 v2, 0, v32, s[78:79]
	s_cbranch_vccnz .LBB0_730
	v_mul_f32_e32 v2, v2, v181
	s_branch .LBB0_730

; #define LAS __attribute__((address_space(3)))
; __device__ __forceinline__ void tr_load(const TrItem& t, float (&v)[32], int lane) {
;     const int n = lane & 31, kh = lane >> 5; const float* wp = t.W + (size_t)(t.k0 + kh) * t.ldw + t.n0 + (n < t.nvalid ? n : 0);
; #pragma unroll
;     for (int i = 0; i < 32; ++i) v[i] = wp[(size_t)(2 * i) * t.ldw];
; }
; __device__ __forceinline__ void tr_finish(const TrItem& t, const float (&v)[32], LAS float* scr, int lane) {
;     const int n = lane & 31, kh = lane >> 5;
; #pragma unroll
;     for (int i = 0; i < 32; ++i) { float x = n < t.nvalid ? v[i] : 0.f; if (t.g) x *= t.g[t.k0 + 2 * i + kh]; scr[(2 * i + kh) * 33 + n] = x; }
.LBB0_1355:
	v_add_u32_e32 v6, s54, v1
	v_ashrrev_i32_e32 v7, 31, v6
	v_mul_lo_u32 v2, s76, v7
	v_mul_lo_u32 v5, s77, v6
	s_waitcnt vmcnt(38)
	v_mad_u64_u32 v[34:35], s[0:1], s76, v6, 0
	v_add3_u32 v35, v35, v2, v5
	v_lshl_add_u64 v[34:35], v[34:35], 2, s[6:7]
	s_ashr_i32 s9, s8, 31
	v_cndmask_b32_e64 v2, 0, v0, s[78:79]
	v_lshl_add_u64 v[34:35], s[8:9], 2, v[34:35]
	v_lshlrev_b32_e32 v2, 2, v2
	v_lshl_add_u64 v[34:35], v[34:35], 0, v[2:3]
	s_lshl_b64 s[0:1], s[76:77], 3
	v_lshl_add_u64 v[62:63], v[34:35], 0, s[0:1]
	v_lshl_add_u64 v[66:67], v[62:63], 0, s[0:1]
	v_lshl_add_u64 v[68:69], v[66:67], 0, s[0:1]
	v_lshl_add_u64 v[70:71], v[68:69], 0, s[0:1]
	v_lshl_add_u64 v[78:79], v[70:71], 0, s[0:1]
	v_lshl_add_u64 v[80:81], v[78:79], 0, s[0:1]
	v_lshl_add_u64 v[82:83], v[80:81], 0, s[0:1]
	global_load_dword v77, v[34:35], off
	global_load_dword v76, v[62:63], off
	global_load_dword v75, v[66:67], off
	global_load_dword v74, v[68:69], off
	global_load_dword v73, v[70:71], off
	global_load_dword v72, v[78:79], off
	s_nop 0
	global_load_dword v71, v[80:81], off
	global_load_dword v70, v[82:83], off
	v_lshl_add_u64 v[34:35], v[82:83], 0, s[0:1]
	global_load_dword v69, v[34:35], off
	v_lshl_add_u64 v[34:35], v[34:35], 0, s[0:1]
	global_load_dword v68, v[34:35], off
	v_lshl_add_u64 v[34:35], v[34:35], 0, s[0:1]
	global_load_dword v67, v[34:35], off
	v_lshl_add_u64 v[34:35], v[34:35], 0, s[0:1]
	global_load_dword v66, v[34:35], off
	v_lshl_add_u64 v[34:35], v[34:35], 0, s[0:1]
	global_load_dword v65, v[34:35], off
	v_lshl_add_u64 v[34:35], v[34:35], 0, s[0:1]
	global_load_dword v63, v[34:35], off
	v_lshl_add_u64 v[34:35], v[34:35], 0, s[0:1]
	global_load_dword v62, v[34:35], off
	v_lshl_add_u64 v[34:35], v[34:35], 0, s[0:1]
	global_load_dword v60, v[34:35], off
	v_lshl_add_u64 v[34:35], v[34:35], 0, s[0:1]
	global_load_dword v58, v[34:35], off
	v_lshl_add_u64 v[34:35], v[34:35], 0, s[0:1]
	global_load_dword v56, v[34:35], off
	v_lshl_add_u64 v[34:35], v[34:35], 0, s[0:1]
	global_load_dword v54, v[34:35], off
	v_lshl_add_u64 v[34:35], v[34:35], 0, s[0:1]
	global_load_dword v53, v[34:35], off
	v_lshl_add_u64 v[34:35], v[34:35], 0, s[0:1]
	global_load_dword v51, v[34:35], off
	v_lshl_add_u64 v[34:35], v[34:35], 0, s[0:1]
	global_load_dword v49, v[34:35], off
	v_lshl_add_u64 v[34:35], v[34:35], 0, s[0:1]
	global_load_dword v47, v[34:35], off
	v_lshl_add_u64 v[34:35], v[34:35], 0, s[0:1]
	global_load_dword v45, v[34:35], off
	v_lshl_add_u64 v[34:35], v[34:35], 0, s[0:1]
	global_load_dword v43, v[34:35], off
	v_lshl_add_u64 v[34:35], v[34:35], 0, s[0:1]
	global_load_dword v41, v[34:35], off
	v_lshl_add_u64 v[34:35], v[34:35], 0, s[0:1]
	global_load_dword v39, v[34:35], off
	v_lshl_add_u64 v[34:35], v[34:35], 0, s[0:1]
	v_lshl_add_u64 v[78:79], v[34:35], 0, s[0:1]
	global_load_dword v37, v[34:35], off
	s_nop 0
	global_load_dword v35, v[78:79], off
	v_lshl_add_u64 v[78:79], v[78:79], 0, s[0:1]
	global_load_dword v34, v[78:79], off
	v_lshl_add_u64 v[78:79], v[78:79], 0, s[0:1]
	global_load_dword v32, v[78:79], off
	v_lshl_add_u64 v[78:79], v[78:79], 0, s[0:1]
	global_load_dword v30, v[78:79], off
	s_cmp_lg_u64 s[46:47], 0
	v_add_u32_e32 v8, s50, v1
	v_cmp_gt_u32_e64 s[6:7], s51, v0
	s_cselect_b64 s[0:1], -1, 0
	s_cmp_eq_u64 s[46:47], 0
	s_waitcnt vmcnt(62)
	v_cndmask_b32_e64 v2, 0, v9, s[6:7]
	v_ashrrev_i32_e32 v9, 31, v8
	s_cbranch_scc1 .LBB0_1357
	v_lshl_add_u64 v[78:79], v[8:9], 2, s[46:47]
	global_load_dword v150, v[78:79], off
	global_load_dword v151, v[78:79], off offset:8
	global_load_dword v152, v[78:79], off offset:16
	global_load_dword v153, v[78:79], off offset:24
	global_load_dword v154, v[78:79], off offset:32
	global_load_dword v155, v[78:79], off offset:40
	global_load_dword v156, v[78:79], off offset:48
	global_load_dword v157, v[78:79], off offset:56
	global_load_dword v158, v[78:79], off offset:64
	global_load_dword v159, v[78:79], off offset:72
	global_load_dword v160, v[78:79], off offset:80
	global_load_dword v161, v[78:79], off offset:88
	global_load_dword v162, v[78:79], off offset:96
	global_load_dword v163, v[78:79], off offset:104
	global_load_dword v164, v[78:79], off offset:112
	global_load_dword v165, v[78:79], off offset:120
	global_load_dword v166, v[78:79], off offset:128
	global_load_dword v167, v[78:79], off offset:136
	global_load_dword v168, v[78:79], off offset:144
	global_load_dword v169, v[78:79], off offset:152
	global_load_dword v170, v[78:79], off offset:160
	global_load_dword v171, v[78:79], off offset:168
	global_load_dword v172, v[78:79], off offset:176
	global_load_dword v173, v[78:79], off offset:184
	global_load_dword v174, v[78:79], off offset:192
	global_load_dword v175, v[78:79], off offset:200
	global_load_dword v176, v[78:79], off offset:208
	global_load_dword v177, v[78:79], off offset:216
	global_load_dword v178, v[78:79], off offset:224
	global_load_dword v179, v[78:79], off offset:232
	global_load_dword v180, v[78:79], off offset:240
	global_load_dword v181, v[78:79], off offset:248
	s_waitcnt vmcnt(0)
	v_mul_f32_e32 v2, v2, v150
.LBB0_1357:
	ds_write_b32 v14, v2
	v_cndmask_b32_e64 v2, 0, 1, s[0:1]
	v_cmp_ne_u32_e64 s[8:9], 1, v2
	s_andn2_b64 vcc, exec, s[0:1]
	v_cndmask_b32_e64 v2, 0, v64, s[6:7]
	s_cbranch_vccnz .LBB0_1359
	v_lshl_add_u64 v[78:79], v[8:9], 2, s[46:47]
	v_mul_f32_e32 v2, v2, v151
.LBB0_1359:
	ds_write_b32 v14, v2 offset:264
	s_and_b64 vcc, exec, s[8:9]
	s_waitcnt vmcnt(61)
	v_cndmask_b32_e64 v2, 0, v61, s[6:7]
	s_cbranch_vccnz .LBB0_1361
	v_lshl_add_u64 v[78:79], v[8:9], 2, s[46:47]
	v_mul_f32_e32 v2, v2, v152
; #define LAS __attribute__((address_space(3)))
; __device__ __forceinline__ void tr_finish(const TrItem& t, const float (&v)[32], LAS float* scr, int lane) {
;     const int n = lane & 31, kh = lane >> 5;
; #pragma unroll
;     for (int i = 0; i < 32; ++i) { float x = n < t.nvalid ? v[i] : 0.f; if (t.g) x *= t.g[t.k0 + 2 * i + kh]; scr[(2 * i + kh) * 33 + n] = x; }
.LBB0_1361:
	ds_write_b32 v14, v2 offset:528
	s_and_b64 vcc, exec, s[8:9]
	s_waitcnt vmcnt(60)
	v_cndmask_b32_e64 v2, 0, v59, s[6:7]
	s_cbranch_vccnz .LBB0_1363
	v_lshl_add_u64 v[78:79], v[8:9], 2, s[46:47]
	v_mul_f32_e32 v2, v2, v153
.LBB0_1363:
	ds_write_b32 v14, v2 offset:792
	s_and_b64 vcc, exec, s[8:9]
	s_waitcnt vmcnt(59)
	v_cndmask_b32_e64 v2, 0, v57, s[6:7]
	s_cbranch_vccnz .LBB0_1365
	v_lshl_add_u64 v[78:79], v[8:9], 2, s[46:47]
	v_mul_f32_e32 v2, v2, v154
.LBB0_1365:
	ds_write_b32 v14, v2 offset:1056
	s_and_b64 vcc, exec, s[8:9]
	s_waitcnt vmcnt(58)
	v_cndmask_b32_e64 v2, 0, v55, s[6:7]
	s_cbranch_vccnz .LBB0_1367
	v_lshl_add_u64 v[78:79], v[8:9], 2, s[46:47]
	v_mul_f32_e32 v2, v2, v155
.LBB0_1367:
	ds_write_b32 v14, v2 offset:1320
	s_and_b64 vcc, exec, s[8:9]
	s_waitcnt vmcnt(57)
	v_cndmask_b32_e64 v2, 0, v52, s[6:7]
	s_cbranch_vccnz .LBB0_1369
	v_lshl_add_u64 v[78:79], v[8:9], 2, s[46:47]
	v_mul_f32_e32 v2, v2, v156
.LBB0_1369:
	ds_write_b32 v14, v2 offset:1584
	s_and_b64 vcc, exec, s[8:9]
	s_waitcnt vmcnt(56)
	v_cndmask_b32_e64 v2, 0, v50, s[6:7]
	s_cbranch_vccnz .LBB0_1371
	v_lshl_add_u64 v[78:79], v[8:9], 2, s[46:47]
	v_mul_f32_e32 v2, v2, v157
.LBB0_1371:
	ds_write_b32 v14, v2 offset:1848
	s_and_b64 vcc, exec, s[8:9]
	s_waitcnt vmcnt(55)
	v_cndmask_b32_e64 v2, 0, v48, s[6:7]
	s_cbranch_vccnz .LBB0_1373
	v_lshl_add_u64 v[78:79], v[8:9], 2, s[46:47]
	v_mul_f32_e32 v2, v2, v158
.LBB0_1373:
	ds_write_b32 v14, v2 offset:2112
	s_and_b64 vcc, exec, s[8:9]
	s_waitcnt vmcnt(54)
	v_cndmask_b32_e64 v2, 0, v46, s[6:7]
	s_cbranch_vccnz .LBB0_1375
	v_lshl_add_u64 v[78:79], v[8:9], 2, s[46:47]
	v_mul_f32_e32 v2, v2, v159
.LBB0_1375:
	ds_write_b32 v14, v2 offset:2376
	s_and_b64 vcc, exec, s[8:9]
	s_waitcnt vmcnt(53)
	v_cndmask_b32_e64 v2, 0, v44, s[6:7]
	s_cbranch_vccnz .LBB0_1377
	v_lshl_add_u64 v[78:79], v[8:9], 2, s[46:47]
	v_mul_f32_e32 v2, v2, v160
.LBB0_1377:
	ds_write_b32 v14, v2 offset:2640
	s_and_b64 vcc, exec, s[8:9]
	s_waitcnt vmcnt(52)
	v_cndmask_b32_e64 v2, 0, v42, s[6:7]
	s_cbranch_vccnz .LBB0_1379
	v_lshl_add_u64 v[78:79], v[8:9], 2, s[46:47]
	v_mul_f32_e32 v2, v2, v161
.LBB0_1379:
	ds_write_b32 v14, v2 offset:2904
	s_and_b64 vcc, exec, s[8:9]
	s_waitcnt vmcnt(51)
	v_cndmask_b32_e64 v2, 0, v40, s[6:7]
	s_cbranch_vccnz .LBB0_1381
	v_lshl_add_u64 v[78:79], v[8:9], 2, s[46:47]
	v_mul_f32_e32 v2, v2, v162
.LBB0_1381:
	ds_write_b32 v14, v2 offset:3168
	s_and_b64 vcc, exec, s[8:9]
	s_waitcnt vmcnt(50)
	v_cndmask_b32_e64 v2, 0, v38, s[6:7]
	s_cbranch_vccnz .LBB0_1383
	v_lshl_add_u64 v[78:79], v[8:9], 2, s[46:47]
	v_mul_f32_e32 v2, v2, v163
.LBB0_1383:
	ds_write_b32 v14, v2 offset:3432
	s_and_b64 vcc, exec, s[8:9]
	s_waitcnt vmcnt(49)
	v_cndmask_b32_e64 v2, 0, v36, s[6:7]
	s_cbranch_vccnz .LBB0_1385
	v_lshl_add_u64 v[78:79], v[8:9], 2, s[46:47]
	v_mul_f32_e32 v2, v2, v164
.LBB0_1385:
	ds_write_b32 v14, v2 offset:3696
	s_and_b64 vcc, exec, s[8:9]
	s_waitcnt vmcnt(48)
	v_cndmask_b32_e64 v2, 0, v33, s[6:7]
	s_cbranch_vccnz .LBB0_1387
	v_lshl_add_u64 v[78:79], v[8:9], 2, s[46:47]
	v_mul_f32_e32 v2, v2, v165
.LBB0_1387:
	ds_write_b32 v14, v2 offset:3960
	s_and_b64 vcc, exec, s[8:9]
	s_waitcnt vmcnt(47)
	v_cndmask_b32_e64 v2, 0, v31, s[6:7]
	s_cbranch_vccnz .LBB0_1389
	v_lshl_add_u64 v[78:79], v[8:9], 2, s[46:47]
	v_mul_f32_e32 v2, v2, v166
.LBB0_1389:
	ds_write_b32 v14, v2 offset:4224
	s_and_b64 vcc, exec, s[8:9]
	s_waitcnt vmcnt(46)
	v_cndmask_b32_e64 v2, 0, v29, s[6:7]
	s_cbranch_vccnz .LBB0_1391
	v_lshl_add_u64 v[78:79], v[8:9], 2, s[46:47]
	v_mul_f32_e32 v2, v2, v167
.LBB0_1391:
	ds_write_b32 v14, v2 offset:4488
	s_and_b64 vcc, exec, s[8:9]
	s_waitcnt vmcnt(45)
	v_cndmask_b32_e64 v2, 0, v28, s[6:7]
	s_cbranch_vccnz .LBB0_1393
	v_lshl_add_u64 v[28:29], v[8:9], 2, s[46:47]
	v_mul_f32_e32 v2, v2, v168
.LBB0_1393:
	ds_write_b32 v14, v2 offset:4752
	s_and_b64 vcc, exec, s[8:9]
	s_waitcnt vmcnt(44)
	v_cndmask_b32_e64 v2, 0, v27, s[6:7]
	s_cbranch_vccnz .LBB0_1395
	v_lshl_add_u64 v[28:29], v[8:9], 2, s[46:47]
	v_mul_f32_e32 v2, v2, v169
.LBB0_1395:
	ds_write_b32 v14, v2 offset:5016
	s_and_b64 vcc, exec, s[8:9]
	s_waitcnt vmcnt(43)
	v_cndmask_b32_e64 v2, 0, v26, s[6:7]
	s_cbranch_vccnz .LBB0_1397
	v_lshl_add_u64 v[26:27], v[8:9], 2, s[46:47]
	v_mul_f32_e32 v2, v2, v170
.LBB0_1397:
	ds_write_b32 v14, v2 offset:5280
	s_and_b64 vcc, exec, s[8:9]
	s_waitcnt vmcnt(42)
	v_cndmask_b32_e64 v2, 0, v25, s[6:7]
	s_cbranch_vccnz .LBB0_1399
	v_lshl_add_u64 v[26:27], v[8:9], 2, s[46:47]
	v_mul_f32_e32 v2, v2, v171
.LBB0_1399:
	ds_write_b32 v14, v2 offset:5544
	s_and_b64 vcc, exec, s[8:9]
	s_waitcnt vmcnt(41)
	v_cndmask_b32_e64 v2, 0, v24, s[6:7]
	s_cbranch_vccnz .LBB0_1401
	v_lshl_add_u64 v[24:25], v[8:9], 2, s[46:47]
	v_mul_f32_e32 v2, v2, v172
.LBB0_1401:
	ds_write_b32 v14, v2 offset:5808
	s_and_b64 vcc, exec, s[8:9]
	s_waitcnt vmcnt(40)
	v_cndmask_b32_e64 v2, 0, v23, s[6:7]
	s_cbranch_vccnz .LBB0_1403
	v_lshl_add_u64 v[24:25], v[8:9], 2, s[46:47]
	v_mul_f32_e32 v2, v2, v173
.LBB0_1403:
	ds_write_b32 v14, v2 offset:6072
	s_and_b64 vcc, exec, s[8:9]
	s_waitcnt vmcnt(39)
	v_cndmask_b32_e64 v2, 0, v22, s[6:7]
	s_cbranch_vccnz .LBB0_1405
	v_lshl_add_u64 v[22:23], v[8:9], 2, s[46:47]
	v_mul_f32_e32 v2, v2, v174
.LBB0_1405:
	ds_write_b32 v14, v2 offset:6336
	s_and_b64 vcc, exec, s[8:9]
	s_waitcnt vmcnt(38)
	v_cndmask_b32_e64 v2, 0, v21, s[6:7]
	s_cbranch_vccnz .LBB0_1407
	v_lshl_add_u64 v[22:23], v[8:9], 2, s[46:47]
	v_mul_f32_e32 v2, v2, v175
.LBB0_1407:
	ds_write_b32 v14, v2 offset:6600
	s_and_b64 vcc, exec, s[8:9]
	s_waitcnt vmcnt(37)
	v_cndmask_b32_e64 v2, 0, v20, s[6:7]
	s_cbranch_vccnz .LBB0_1409
	v_lshl_add_u64 v[20:21], v[8:9], 2, s[46:47]
	v_mul_f32_e32 v2, v2, v176
.LBB0_1409:
	ds_write_b32 v14, v2 offset:6864
	s_and_b64 vcc, exec, s[8:9]
	s_waitcnt vmcnt(36)
	v_cndmask_b32_e64 v2, 0, v19, s[6:7]
	s_cbranch_vccnz .LBB0_1411
	v_lshl_add_u64 v[20:21], v[8:9], 2, s[46:47]
	v_mul_f32_e32 v2, v2, v177
.LBB0_1411:
	ds_write_b32 v14, v2 offset:7128
	s_and_b64 vcc, exec, s[8:9]
	s_waitcnt vmcnt(35)
	v_cndmask_b32_e64 v2, 0, v18, s[6:7]
	s_cbranch_vccnz .LBB0_1413
	v_lshl_add_u64 v[18:19], v[8:9], 2, s[46:47]
	v_mul_f32_e32 v2, v2, v178
.LBB0_1413:
	ds_write_b32 v14, v2 offset:7392
	s_and_b64 vcc, exec, s[8:9]
	s_waitcnt vmcnt(34)
	v_cndmask_b32_e64 v2, 0, v17, s[6:7]
	s_cbranch_vccnz .LBB0_1415
	v_lshl_add_u64 v[18:19], v[8:9], 2, s[46:47]
	v_mul_f32_e32 v2, v2, v179
.LBB0_1415:
	ds_write_b32 v14, v2 offset:7656
	s_and_b64 vcc, exec, s[8:9]
	s_waitcnt vmcnt(33)
	v_cndmask_b32_e64 v2, 0, v16, s[6:7]
	s_cbranch_vccnz .LBB0_1417
	v_lshl_add_u64 v[16:17], v[8:9], 2, s[46:47]
	v_mul_f32_e32 v2, v2, v180
.LBB0_1417:
	ds_write_b32 v14, v2 offset:7920
	s_and_b64 vcc, exec, s[8:9]
	s_waitcnt vmcnt(32)
	v_cndmask_b32_e64 v2, 0, v15, s[6:7]
	s_cbranch_vccnz .LBB0_1419
	v_lshl_add_u64 v[8:9], v[8:9], 2, s[46:47]
	v_mul_f32_e32 v2, v2, v181

; #define LAS __attribute__((address_space(3)))
; __device__ __forceinline__ void tr_load(const TrItem& t, float (&v)[32], int lane) {
;     const int n = lane & 31, kh = lane >> 5; const float* wp = t.W + (size_t)(t.k0 + kh) * t.ldw + t.n0 + (n < t.nvalid ? n : 0);
; #pragma unroll
;     for (int i = 0; i < 32; ++i) v[i] = wp[(size_t)(2 * i) * t.ldw];
; }
; __device__ __forceinline__ void tr_finish(const TrItem& t, const float (&v)[32], LAS float* scr, int lane) {
;     const int n = lane & 31, kh = lane >> 5;
; #pragma unroll
;     for (int i = 0; i < 32; ++i) { float x = n < t.nvalid ? v[i] : 0.f; if (t.g) x *= t.g[t.k0 + 2 * i + kh]; scr[(2 * i + kh) * 33 + n] = x; }
.LBB0_1445:
	v_add_u32_e32 v2, s50, v1
	v_ashrrev_i32_e32 v5, 31, v2
	v_mul_lo_u32 v5, s74, v5
	v_mul_lo_u32 v15, s75, v2
	v_mad_u64_u32 v[8:9], s[0:1], s74, v2, 0
	v_add3_u32 v9, v9, v5, v15
	v_cmp_gt_u32_e32 vcc, s51, v0
	v_lshl_add_u64 v[8:9], v[8:9], 2, s[6:7]
	s_ashr_i32 s9, s8, 31
	v_cndmask_b32_e32 v2, 0, v0, vcc
	v_lshl_add_u64 v[8:9], s[8:9], 2, v[8:9]
	v_lshlrev_b32_e32 v2, 2, v2
	v_lshl_add_u64 v[8:9], v[8:9], 0, v[2:3]
	s_lshl_b64 s[0:1], s[74:75], 3
	v_lshl_add_u64 v[16:17], v[8:9], 0, s[0:1]
	v_lshl_add_u64 v[18:19], v[16:17], 0, s[0:1]
	v_lshl_add_u64 v[20:21], v[18:19], 0, s[0:1]
	v_lshl_add_u64 v[22:23], v[20:21], 0, s[0:1]
	v_lshl_add_u64 v[24:25], v[22:23], 0, s[0:1]
	v_lshl_add_u64 v[26:27], v[24:25], 0, s[0:1]
	v_lshl_add_u64 v[28:29], v[26:27], 0, s[0:1]
	global_load_dword v9, v[8:9], off
	s_nop 0
	global_load_dword v64, v[16:17], off
	global_load_dword v61, v[18:19], off
	global_load_dword v59, v[20:21], off
	global_load_dword v57, v[22:23], off
	global_load_dword v55, v[24:25], off
	global_load_dword v52, v[26:27], off
	global_load_dword v50, v[28:29], off
	v_lshl_add_u64 v[16:17], v[28:29], 0, s[0:1]
	global_load_dword v48, v[16:17], off
	v_lshl_add_u64 v[16:17], v[16:17], 0, s[0:1]
	global_load_dword v46, v[16:17], off
	v_lshl_add_u64 v[16:17], v[16:17], 0, s[0:1]
	global_load_dword v44, v[16:17], off
	v_lshl_add_u64 v[16:17], v[16:17], 0, s[0:1]
	global_load_dword v42, v[16:17], off
	v_lshl_add_u64 v[16:17], v[16:17], 0, s[0:1]
	global_load_dword v40, v[16:17], off
	v_lshl_add_u64 v[16:17], v[16:17], 0, s[0:1]
	global_load_dword v38, v[16:17], off
	v_lshl_add_u64 v[16:17], v[16:17], 0, s[0:1]
	global_load_dword v36, v[16:17], off
	v_lshl_add_u64 v[16:17], v[16:17], 0, s[0:1]
	global_load_dword v33, v[16:17], off
	v_lshl_add_u64 v[16:17], v[16:17], 0, s[0:1]
	global_load_dword v31, v[16:17], off
	v_lshl_add_u64 v[16:17], v[16:17], 0, s[0:1]
	global_load_dword v29, v[16:17], off
	v_lshl_add_u64 v[16:17], v[16:17], 0, s[0:1]
	global_load_dword v28, v[16:17], off
	v_lshl_add_u64 v[16:17], v[16:17], 0, s[0:1]
	global_load_dword v27, v[16:17], off
	v_lshl_add_u64 v[16:17], v[16:17], 0, s[0:1]
	global_load_dword v26, v[16:17], off
	v_lshl_add_u64 v[16:17], v[16:17], 0, s[0:1]
	global_load_dword v25, v[16:17], off
	v_lshl_add_u64 v[16:17], v[16:17], 0, s[0:1]
	global_load_dword v24, v[16:17], off
	v_lshl_add_u64 v[16:17], v[16:17], 0, s[0:1]
	global_load_dword v23, v[16:17], off
	v_lshl_add_u64 v[16:17], v[16:17], 0, s[0:1]
	global_load_dword v22, v[16:17], off
	v_lshl_add_u64 v[16:17], v[16:17], 0, s[0:1]
	global_load_dword v21, v[16:17], off
	v_lshl_add_u64 v[16:17], v[16:17], 0, s[0:1]
	global_load_dword v20, v[16:17], off
	v_lshl_add_u64 v[16:17], v[16:17], 0, s[0:1]
	global_load_dword v19, v[16:17], off
	v_lshl_add_u64 v[16:17], v[16:17], 0, s[0:1]
	v_lshl_add_u64 v[78:79], v[16:17], 0, s[0:1]
	global_load_dword v18, v[16:17], off
	s_nop 0
	global_load_dword v17, v[78:79], off
	v_lshl_add_u64 v[78:79], v[78:79], 0, s[0:1]
	global_load_dword v16, v[78:79], off
	v_lshl_add_u64 v[78:79], v[78:79], 0, s[0:1]
	global_load_dword v15, v[78:79], off
	s_andn2_b64 vcc, exec, s[82:83]
	s_cbranch_vccnz .LBB0_1328
	s_cmp_lg_u64 s[84:85], 0
	s_cselect_b64 s[0:1], -1, 0
	s_cmp_eq_u64 s[84:85], 0
	s_waitcnt vmcnt(62)
	v_cndmask_b32_e64 v2, 0, v77, s[78:79]
	v_lshl_add_u64 v[6:7], v[6:7], 2, s[84:85]
	s_cbranch_scc1 .LBB0_1448
	global_load_dword v150, v[6:7], off
	global_load_dword v151, v[6:7], off offset:8
	global_load_dword v152, v[6:7], off offset:16
	global_load_dword v153, v[6:7], off offset:24
	global_load_dword v154, v[6:7], off offset:32
	global_load_dword v155, v[6:7], off offset:40
	global_load_dword v156, v[6:7], off offset:48
	global_load_dword v157, v[6:7], off offset:56
	global_load_dword v158, v[6:7], off offset:64
	global_load_dword v159, v[6:7], off offset:72
	global_load_dword v160, v[6:7], off offset:80
	global_load_dword v161, v[6:7], off offset:88
	global_load_dword v162, v[6:7], off offset:96
	global_load_dword v163, v[6:7], off offset:104
	global_load_dword v164, v[6:7], off offset:112
	global_load_dword v165, v[6:7], off offset:120
	global_load_dword v166, v[6:7], off offset:128
	global_load_dword v167, v[6:7], off offset:136
	global_load_dword v168, v[6:7], off offset:144
	global_load_dword v169, v[6:7], off offset:152
	global_load_dword v170, v[6:7], off offset:160
	global_load_dword v171, v[6:7], off offset:168
	global_load_dword v172, v[6:7], off offset:176
	global_load_dword v173, v[6:7], off offset:184
	global_load_dword v174, v[6:7], off offset:192
	global_load_dword v175, v[6:7], off offset:200
	global_load_dword v176, v[6:7], off offset:208
	global_load_dword v177, v[6:7], off offset:216
	global_load_dword v178, v[6:7], off offset:224
	global_load_dword v179, v[6:7], off offset:232
	global_load_dword v180, v[6:7], off offset:240
	global_load_dword v181, v[6:7], off offset:248
	s_waitcnt vmcnt(0)
	v_mul_f32_e32 v2, v2, v150
.LBB0_1448:
	ds_write_b32 v14, v2
	v_cndmask_b32_e64 v2, 0, 1, s[0:1]
	v_cmp_ne_u32_e64 s[6:7], 1, v2
	s_andn2_b64 vcc, exec, s[0:1]
	v_cndmask_b32_e64 v2, 0, v76, s[78:79]
	s_cbranch_vccnz .LBB0_1450
	v_mul_f32_e32 v2, v2, v151
.LBB0_1450:
	ds_write_b32 v14, v2 offset:264
	s_and_b64 vcc, exec, s[6:7]
	v_cndmask_b32_e64 v2, 0, v75, s[78:79]
	s_cbranch_vccnz .LBB0_1452
	v_mul_f32_e32 v2, v2, v152
; #define LAS __attribute__((address_space(3)))
; __device__ __forceinline__ void tr_finish(const TrItem& t, const float (&v)[32], LAS float* scr, int lane) {
;     const int n = lane & 31, kh = lane >> 5;
; #pragma unroll
;     for (int i = 0; i < 32; ++i) { float x = n < t.nvalid ? v[i] : 0.f; if (t.g) x *= t.g[t.k0 + 2 * i + kh]; scr[(2 * i + kh) * 33 + n] = x; }
.LBB0_1452:
	ds_write_b32 v14, v2 offset:528
	s_and_b64 vcc, exec, s[6:7]
	v_cndmask_b32_e64 v2, 0, v74, s[78:79]
	s_cbranch_vccnz .LBB0_1454
	v_mul_f32_e32 v2, v2, v153
.LBB0_1454:
	ds_write_b32 v14, v2 offset:792
	s_and_b64 vcc, exec, s[6:7]
	v_cndmask_b32_e64 v2, 0, v73, s[78:79]
	s_cbranch_vccnz .LBB0_1456
	v_mul_f32_e32 v2, v2, v154
.LBB0_1456:
	ds_write_b32 v14, v2 offset:1056
	s_and_b64 vcc, exec, s[6:7]
	v_cndmask_b32_e64 v2, 0, v72, s[78:79]
	s_cbranch_vccnz .LBB0_1458
	v_mul_f32_e32 v2, v2, v155
.LBB0_1458:
	ds_write_b32 v14, v2 offset:1320
	s_and_b64 vcc, exec, s[6:7]
	s_waitcnt vmcnt(61)
	v_cndmask_b32_e64 v2, 0, v71, s[78:79]
	s_cbranch_vccnz .LBB0_1460
	v_mul_f32_e32 v2, v2, v156
.LBB0_1460:
	ds_write_b32 v14, v2 offset:1584
	s_and_b64 vcc, exec, s[6:7]
	s_waitcnt vmcnt(60)
	v_cndmask_b32_e64 v2, 0, v70, s[78:79]
	s_cbranch_vccnz .LBB0_1462
	v_mul_f32_e32 v2, v2, v157
.LBB0_1462:
	ds_write_b32 v14, v2 offset:1848
	s_and_b64 vcc, exec, s[6:7]
	s_waitcnt vmcnt(59)
	v_cndmask_b32_e64 v2, 0, v69, s[78:79]
	s_cbranch_vccnz .LBB0_1464
	v_mul_f32_e32 v2, v2, v158
.LBB0_1464:
	ds_write_b32 v14, v2 offset:2112
	s_and_b64 vcc, exec, s[6:7]
	s_waitcnt vmcnt(58)
	v_cndmask_b32_e64 v2, 0, v68, s[78:79]
	s_cbranch_vccnz .LBB0_1466
	v_mul_f32_e32 v2, v2, v159
.LBB0_1466:
	ds_write_b32 v14, v2 offset:2376
	s_and_b64 vcc, exec, s[6:7]
	s_waitcnt vmcnt(57)
	v_cndmask_b32_e64 v2, 0, v67, s[78:79]
	s_cbranch_vccnz .LBB0_1468
	v_mul_f32_e32 v2, v2, v160
.LBB0_1468:
	ds_write_b32 v14, v2 offset:2640
	s_and_b64 vcc, exec, s[6:7]
	s_waitcnt vmcnt(56)
	v_cndmask_b32_e64 v2, 0, v66, s[78:79]
	s_cbranch_vccnz .LBB0_1470
	v_mul_f32_e32 v2, v2, v161
.LBB0_1470:
	ds_write_b32 v14, v2 offset:2904
	s_and_b64 vcc, exec, s[6:7]
	s_waitcnt vmcnt(55)
	v_cndmask_b32_e64 v2, 0, v65, s[78:79]
	s_cbranch_vccnz .LBB0_1472
	v_mul_f32_e32 v2, v2, v162
.LBB0_1472:
	ds_write_b32 v14, v2 offset:3168
	s_and_b64 vcc, exec, s[6:7]
	s_waitcnt vmcnt(54)
	v_cndmask_b32_e64 v2, 0, v63, s[78:79]
	s_cbranch_vccnz .LBB0_1474
	v_mul_f32_e32 v2, v2, v163
.LBB0_1474:
	ds_write_b32 v14, v2 offset:3432
	s_and_b64 vcc, exec, s[6:7]
	s_waitcnt vmcnt(53)
	v_cndmask_b32_e64 v2, 0, v62, s[78:79]
	s_cbranch_vccnz .LBB0_1476
	v_mul_f32_e32 v2, v2, v164
.LBB0_1476:
	ds_write_b32 v14, v2 offset:3696
	s_and_b64 vcc, exec, s[6:7]
	s_waitcnt vmcnt(52)
	v_cndmask_b32_e64 v2, 0, v60, s[78:79]
	s_cbranch_vccnz .LBB0_1478
	v_mul_f32_e32 v2, v2, v165
.LBB0_1478:
	ds_write_b32 v14, v2 offset:3960
	s_and_b64 vcc, exec, s[6:7]
	s_waitcnt vmcnt(51)
	v_cndmask_b32_e64 v2, 0, v58, s[78:79]
	s_cbranch_vccnz .LBB0_1480
	v_mul_f32_e32 v2, v2, v166
.LBB0_1480:
	ds_write_b32 v14, v2 offset:4224
	s_and_b64 vcc, exec, s[6:7]
	s_waitcnt vmcnt(50)
	v_cndmask_b32_e64 v2, 0, v56, s[78:79]
	s_cbranch_vccnz .LBB0_1482
	v_mul_f32_e32 v2, v2, v167
.LBB0_1482:
	ds_write_b32 v14, v2 offset:4488
	s_and_b64 vcc, exec, s[6:7]
	s_waitcnt vmcnt(49)
	v_cndmask_b32_e64 v2, 0, v54, s[78:79]
	s_cbranch_vccnz .LBB0_1484
	v_mul_f32_e32 v2, v2, v168
.LBB0_1484:
	ds_write_b32 v14, v2 offset:4752
	s_and_b64 vcc, exec, s[6:7]
	s_waitcnt vmcnt(48)
	v_cndmask_b32_e64 v2, 0, v53, s[78:79]
	s_cbranch_vccnz .LBB0_1486
	v_mul_f32_e32 v2, v2, v169
.LBB0_1486:
	ds_write_b32 v14, v2 offset:5016
	s_and_b64 vcc, exec, s[6:7]
	s_waitcnt vmcnt(47)
	v_cndmask_b32_e64 v2, 0, v51, s[78:79]
	s_cbranch_vccnz .LBB0_1488
	v_mul_f32_e32 v2, v2, v170
.LBB0_1488:
	ds_write_b32 v14, v2 offset:5280
	s_and_b64 vcc, exec, s[6:7]
	s_waitcnt vmcnt(46)
	v_cndmask_b32_e64 v2, 0, v49, s[78:79]
	s_cbranch_vccnz .LBB0_1490
	v_mul_f32_e32 v2, v2, v171
.LBB0_1490:
	ds_write_b32 v14, v2 offset:5544
	s_and_b64 vcc, exec, s[6:7]
	s_waitcnt vmcnt(45)
	v_cndmask_b32_e64 v2, 0, v47, s[78:79]
	s_cbranch_vccnz .LBB0_1492
	v_mul_f32_e32 v2, v2, v172
.LBB0_1492:
	ds_write_b32 v14, v2 offset:5808
	s_and_b64 vcc, exec, s[6:7]
	s_waitcnt vmcnt(44)
	v_cndmask_b32_e64 v2, 0, v45, s[78:79]
	s_cbranch_vccnz .LBB0_1494
	v_mul_f32_e32 v2, v2, v173
.LBB0_1494:
	ds_write_b32 v14, v2 offset:6072
	s_and_b64 vcc, exec, s[6:7]
	s_waitcnt vmcnt(43)
	v_cndmask_b32_e64 v2, 0, v43, s[78:79]
	s_cbranch_vccnz .LBB0_1496
	v_mul_f32_e32 v2, v2, v174
.LBB0_1496:
	ds_write_b32 v14, v2 offset:6336
	s_and_b64 vcc, exec, s[6:7]
	s_waitcnt vmcnt(42)
	v_cndmask_b32_e64 v2, 0, v41, s[78:79]
	s_cbranch_vccnz .LBB0_1498
	v_mul_f32_e32 v2, v2, v175
.LBB0_1498:
	ds_write_b32 v14, v2 offset:6600
	s_and_b64 vcc, exec, s[6:7]
	s_waitcnt vmcnt(41)
	v_cndmask_b32_e64 v2, 0, v39, s[78:79]
	s_cbranch_vccnz .LBB0_1500
	v_mul_f32_e32 v2, v2, v176
.LBB0_1500:
	ds_write_b32 v14, v2 offset:6864
	s_and_b64 vcc, exec, s[6:7]
	s_waitcnt vmcnt(40)
	v_cndmask_b32_e64 v2, 0, v37, s[78:79]
	s_cbranch_vccnz .LBB0_1502
	v_mul_f32_e32 v2, v2, v177
.LBB0_1502:
	ds_write_b32 v14, v2 offset:7128
	s_and_b64 vcc, exec, s[6:7]
	s_waitcnt vmcnt(39)
	v_cndmask_b32_e64 v2, 0, v35, s[78:79]
	s_cbranch_vccnz .LBB0_1504
	v_mul_f32_e32 v2, v2, v178
.LBB0_1504:
	ds_write_b32 v14, v2 offset:7392
	s_and_b64 vcc, exec, s[6:7]
	s_waitcnt vmcnt(38)
	v_cndmask_b32_e64 v2, 0, v34, s[78:79]
	s_cbranch_vccnz .LBB0_1506
	v_mul_f32_e32 v2, v2, v179
.LBB0_1506:
	ds_write_b32 v14, v2 offset:7656
	s_and_b64 vcc, exec, s[6:7]
	s_waitcnt vmcnt(37)
	v_cndmask_b32_e64 v2, 0, v32, s[78:79]
	s_cbranch_vccnz .LBB0_1508
	v_mul_f32_e32 v2, v2, v180
.LBB0_1508:
	ds_write_b32 v14, v2 offset:7920
	s_and_b64 vcc, exec, s[6:7]
	s_waitcnt vmcnt(36)
	v_cndmask_b32_e64 v2, 0, v30, s[78:79]
	s_cbranch_vccnz .LBB0_1327
	v_mul_f32_e32 v2, v2, v181
	s_branch .LBB0_1327

; __device__ __forceinline__ void attn_sample_item(const SmpArgs& a, int b, int g, LAS unsigned char* lds, int tid) {
;     ...
; #pragma unroll 1
;     ...
;         const unsigned long long gt = __ballot(key > thr); unsigned long long eq = __ballot(key == thr);
;         int need = 16 - __popcll(gt); unsigned long long sel = gt;
.LBB0_2560:
	s_or_b32 s15, s20, 0x40000000
	v_cmp_le_u32_e32 vcc, s15, v2
	s_bcnt1_i32_b64 s54, vcc
	s_cmp_gt_u32 s54, 15
	s_cselect_b32 s20, s15, s20
	s_or_b32 s15, s20, 0x20000000
	v_cmp_le_u32_e32 vcc, s15, v2
	s_bcnt1_i32_b64 s54, vcc
	s_cmp_eq_u32 s54, 16
	s_cbranch_scc1 .Lmy_rs_hit_i
	s_cmp_gt_u32 s54, 15
	s_cselect_b32 s20, s15, s20
	s_or_b32 s15, s20, 0x10000000
	v_cmp_le_u32_e32 vcc, s15, v2
	s_bcnt1_i32_b64 s54, vcc
	s_cmp_gt_u32 s54, 15
	s_cselect_b32 s20, s15, s20
	s_or_b32 s15, s20, 0x8000000
	v_cmp_le_u32_e32 vcc, s15, v2
	s_bcnt1_i32_b64 s54, vcc
	s_cmp_eq_u32 s54, 16
	s_cbranch_scc1 .Lmy_rs_hit_i
	s_cmp_gt_u32 s54, 15
	s_cselect_b32 s20, s15, s20
	s_or_b32 s15, s20, 0x4000000
	v_cmp_le_u32_e32 vcc, s15, v2
	s_bcnt1_i32_b64 s54, vcc
	s_cmp_gt_u32 s54, 15
	s_cselect_b32 s20, s15, s20
	s_or_b32 s15, s20, 0x2000000
	v_cmp_le_u32_e32 vcc, s15, v2
	s_bcnt1_i32_b64 s54, vcc
	s_cmp_eq_u32 s54, 16
	s_cbranch_scc1 .Lmy_rs_hit_i
	s_cmp_gt_u32 s54, 15
	s_cselect_b32 s20, s15, s20
	s_or_b32 s15, s20, 0x1000000
	v_cmp_le_u32_e32 vcc, s15, v2
	s_bcnt1_i32_b64 s54, vcc
	s_cmp_gt_u32 s54, 15
	s_cselect_b32 s20, s15, s20
	s_or_b32 s15, s20, 0x800000
	v_cmp_le_u32_e32 vcc, s15, v2
	s_bcnt1_i32_b64 s54, vcc
	s_cmp_eq_u32 s54, 16
	s_cbranch_scc1 .Lmy_rs_hit_i
	s_cmp_gt_u32 s54, 15
	s_cselect_b32 s20, s15, s20
	s_or_b32 s15, s20, 0x400000
	v_cmp_le_u32_e32 vcc, s15, v2
	s_bcnt1_i32_b64 s54, vcc
	s_cmp_gt_u32 s54, 15
	s_cselect_b32 s20, s15, s20
	s_or_b32 s15, s20, 0x200000
	v_cmp_le_u32_e32 vcc, s15, v2
	s_bcnt1_i32_b64 s54, vcc
	s_cmp_eq_u32 s54, 16
	s_cbranch_scc1 .Lmy_rs_hit_i
	s_cmp_gt_u32 s54, 15
	s_cselect_b32 s20, s15, s20
	s_or_b32 s15, s20, 0x100000
	v_cmp_le_u32_e32 vcc, s15, v2
	s_bcnt1_i32_b64 s54, vcc
	s_cmp_gt_u32 s54, 15
	s_cselect_b32 s20, s15, s20
	s_or_b32 s15, s20, 0x80000
	v_cmp_le_u32_e32 vcc, s15, v2
	s_bcnt1_i32_b64 s54, vcc
	s_cmp_eq_u32 s54, 16
	s_cbranch_scc1 .Lmy_rs_hit_i
	s_cmp_gt_u32 s54, 15
	s_cselect_b32 s20, s15, s20
	s_or_b32 s15, s20, 0x40000
	v_cmp_le_u32_e32 vcc, s15, v2
	s_bcnt1_i32_b64 s54, vcc
	s_cmp_gt_u32 s54, 15
	s_cselect_b32 s20, s15, s20
	s_or_b32 s15, s20, 0x20000
	v_cmp_le_u32_e32 vcc, s15, v2
	s_bcnt1_i32_b64 s54, vcc
	s_cmp_eq_u32 s54, 16
	s_cbranch_scc1 .Lmy_rs_hit_i
	s_cmp_gt_u32 s54, 15
	s_cselect_b32 s20, s15, s20
	s_or_b32 s15, s20, 0x10000
	v_cmp_le_u32_e32 vcc, s15, v2
	s_bcnt1_i32_b64 s54, vcc
	s_cmp_gt_u32 s54, 15
	s_cselect_b32 s20, s15, s20
	s_or_b32 s15, s20, 0x8000
	v_cmp_le_u32_e32 vcc, s15, v2
	s_bcnt1_i32_b64 s54, vcc
	s_cmp_eq_u32 s54, 16
	s_cbranch_scc1 .Lmy_rs_hit_i
	s_cmp_gt_u32 s54, 15
	s_cselect_b32 s20, s15, s20
	s_or_b32 s15, s20, 0x4000
	v_cmp_le_u32_e32 vcc, s15, v2
	s_bcnt1_i32_b64 s54, vcc
	s_cmp_gt_u32 s54, 15
	s_cselect_b32 s20, s15, s20
	s_or_b32 s15, s20, 0x2000
	v_cmp_le_u32_e32 vcc, s15, v2
	s_bcnt1_i32_b64 s54, vcc
	s_cmp_eq_u32 s54, 16
	s_cbranch_scc1 .Lmy_rs_hit_i
	s_cmp_gt_u32 s54, 15
	s_cselect_b32 s20, s15, s20
	s_or_b32 s15, s20, 0x1000
	v_cmp_le_u32_e32 vcc, s15, v2
	s_bcnt1_i32_b64 s54, vcc
	s_cmp_gt_u32 s54, 15
	s_cselect_b32 s20, s15, s20
	s_or_b32 s15, s20, 0x800
	v_cmp_le_u32_e32 vcc, s15, v2
	s_bcnt1_i32_b64 s54, vcc
	s_cmp_eq_u32 s54, 16
	s_cbranch_scc1 .Lmy_rs_hit_i
	s_cmp_gt_u32 s54, 15
	s_cselect_b32 s20, s15, s20
	s_or_b32 s15, s20, 0x400
	v_cmp_le_u32_e32 vcc, s15, v2
	s_bcnt1_i32_b64 s54, vcc
	s_cmp_gt_u32 s54, 15
	s_cselect_b32 s20, s15, s20
	s_or_b32 s15, s20, 0x200
	v_cmp_le_u32_e32 vcc, s15, v2
	s_bcnt1_i32_b64 s54, vcc
	s_cmp_eq_u32 s54, 16
	s_cbranch_scc1 .Lmy_rs_hit_i
	s_cmp_gt_u32 s54, 15
	s_cselect_b32 s20, s15, s20
	s_or_b32 s15, s20, 0x100
	v_cmp_le_u32_e32 vcc, s15, v2
	s_bcnt1_i32_b64 s54, vcc
	s_cmp_gt_u32 s54, 15
	s_cselect_b32 s20, s15, s20
	s_or_b32 s15, s20, 0x80
	v_cmp_le_u32_e32 vcc, s15, v2
	s_bcnt1_i32_b64 s54, vcc
	s_cmp_eq_u32 s54, 16
	s_cbranch_scc1 .Lmy_rs_hit_i
	s_cmp_gt_u32 s54, 15
	s_cselect_b32 s20, s15, s20
	s_or_b32 s15, s20, 64
	v_cmp_le_u32_e32 vcc, s15, v2
	s_bcnt1_i32_b64 s54, vcc
	s_cmp_gt_u32 s54, 15
	s_cselect_b32 s20, s15, s20
	s_or_b32 s15, s20, 32
	v_cmp_le_u32_e32 vcc, s15, v2
	s_bcnt1_i32_b64 s54, vcc
	s_cmp_eq_u32 s54, 16
	s_cbranch_scc1 .Lmy_rs_hit_i
	s_cmp_gt_u32 s54, 15
	s_cselect_b32 s20, s15, s20
	s_or_b32 s15, s20, 16
	v_cmp_le_u32_e32 vcc, s15, v2
	s_bcnt1_i32_b64 s54, vcc
	s_cmp_gt_u32 s54, 15
	s_cselect_b32 s20, s15, s20
	s_or_b32 s15, s20, 8
	v_cmp_le_u32_e32 vcc, s15, v2
	s_bcnt1_i32_b64 s54, vcc
	s_cmp_eq_u32 s54, 16
	s_cbranch_scc1 .Lmy_rs_hit_i
	s_cmp_gt_u32 s54, 15
	s_cselect_b32 s20, s15, s20
	s_or_b32 s15, s20, 4
	v_cmp_le_u32_e32 vcc, s15, v2
	s_bcnt1_i32_b64 s54, vcc
	s_cmp_gt_u32 s54, 15
	s_cselect_b32 s20, s15, s20
	s_or_b32 s15, s20, 2
	v_cmp_le_u32_e32 vcc, s15, v2
	s_bcnt1_i32_b64 s54, vcc
	s_cmp_eq_u32 s54, 16
	s_cbranch_scc1 .Lmy_rs_hit_i
	s_cmp_gt_u32 s54, 15
	s_cselect_b32 s20, s15, s20
	s_or_b32 s15, s20, 1
	v_cmp_le_u32_e32 vcc, s15, v2
	s_bcnt1_i32_b64 s54, vcc
	s_cmp_gt_u32 s54, 15
	s_cselect_b32 s20, s15, s20
	s_branch .Lmy_rs_go_i
.Lmy_rs_hit_i:
	s_mov_b64 s[14:15], vcc
	s_branch .LBB0_2564
.Lmy_rs_go_i:
	v_cmp_lt_u32_e64 s[14:15], s20, v2
	v_cmp_eq_u32_e64 s[20:21], s20, v2
	s_bcnt1_i32_b64 s54, s[14:15]
	s_cmp_eq_u64 s[20:21], 0
	v_cmp_gt_u64_e64 s[22:23], s[54:55], 15
	s_cselect_b64 s[24:25], -1, 0
	s_or_b64 s[22:23], s[22:23], s[24:25]
	s_and_b64 vcc, exec, s[22:23]
	s_cbranch_vccnz .LBB0_2564
	s_sub_i32 s22, 16, s54

; #define LAS __attribute__((address_space(3)))
; template <int CTRL> __device__ __forceinline__ float dpp_mov(float v) { return __int_as_float(__builtin_amdgcn_update_dpp(0, __float_as_int(v), CTRL, 0xF, 0xF, true)); }
; __device__ __forceinline__ void attn_prompt_unit(const AttnArgs& a, int n, int g, int qt, LAS unsigned char* lds, int tid) {
;     ...
;         float cf = (float)c; cf += dpp_mov<0xB1>(cf); cf += dpp_mov<0x4E>(cf); cf += dpp_mov<0x141>(cf);
;         if (cur < 16) { bits = 0u;
; #pragma unroll
;             for (int e = 0; e < 8; ++e) bits |= (8 * sub + e) <= cur ? (1u << e) : 0u; }
;         ((LAS unsigned char*)maskb)[tk8 * 8 + sub] = (unsigned char)bits;
;         const bool ok = cur < 16 || cf == 16.0f;
;         if (!__all(ok)) {
;     ...
;     { int tq = t, hq = h, hhq = hh; asm volatile("" : "+v"(tq), "+v"(hq), "+v"(hhq));
;       const bf16* qp = a.QR + ((size_t)n * SEQ + tq) * D + (4 * g + hq) * 64 + 8 * hhq;
; #pragma unroll
;       for (int st = 0; st < 4; ++st) qf[st] = *(const bf16x8*)(qp + 16 * st); }
.LBB0_2795:
	s_or_b64 exec, exec, s[0:1]
	v_mov_b32_e32 v194, v222
	v_ashrrev_i32_e32 v195, 31, v194
	v_lshl_add_u64 v[194:195], s[26:27], 0, v[194:195]
	v_lshlrev_b64 v[194:195], 11, v[194:195]
	v_lshl_add_u32 v196, v98, 6, s85
	v_lshl_add_u64 v[194:195], s[50:51], 0, v[194:195]
	v_ashrrev_i32_e32 v197, 31, v196
	v_lshl_add_u64 v[194:195], v[196:197], 1, v[194:195]
	v_lshlrev_b32_e32 v196, 3, v216
	v_ashrrev_i32_e32 v197, 31, v196
	v_lshl_add_u64 v[194:195], v[196:197], 1, v[194:195]
	global_load_dwordx4 v[178:181], v[194:195], off
	global_load_dwordx4 v[182:185], v[194:195], off offset:32
	global_load_dwordx4 v[186:189], v[194:195], off offset:64
	global_load_dwordx4 v[190:193], v[194:195], off offset:96
	v_add_f32_e32 v3, v3, v5
	v_cmp_eq_f32_e32 vcc, s69, v3
	s_or_b64 s[0:1], s[24:25], vcc
	v_cndmask_b32_e64 v3, 0, 1, s[0:1]
	v_lshl_add_u32 v6, v100, 3, s41
	v_cmp_ne_u32_e32 vcc, 0, v3
	v_add_u32_e32 v5, v6, v134
	s_cmp_eq_u64 vcc, exec
	ds_write_b8 v5, v7
	s_cbranch_scc1 .LBB0_2807
	v_cmp_eq_u32_e64 s[10:11], 0, v134
	v_cmp_eq_u32_e32 vcc, v134, v0
	s_or_b64 s[0:1], s[10:11], vcc
	v_cmp_eq_u32_e32 vcc, v134, v2
	s_or_b64 vcc, s[0:1], vcc
	v_lshlrev_b64 v[2:3], v0, 2
	v_lshl_add_u32 v7, v134, 2, v4
	s_mov_b32 s18, 0
	v_cmp_gt_i32_e64 s[12:13], v134, v0
	v_cndmask_b32_e32 v8, 0, v230, vcc
	v_lshl_add_u64 v[2:3], v[2:3], 0, -1
	s_branch .LBB0_2798

; __device__ __forceinline__ void attn_prompt_unit(const AttnArgs& a, int n, int g, int qt, LAS unsigned char* lds, int tid) {
;     ...
;                     unsigned thr1 = 0u;
; #pragma unroll 1
.LBB0_2800:
	s_or_b32 s15, s16, 0x40000000
	v_cmp_le_u32_e32 vcc, s15, v0
	s_bcnt1_i32_b64 s54, vcc
	s_cmp_gt_u32 s54, 15
	s_cselect_b32 s16, s15, s16
	s_or_b32 s15, s16, 0x20000000
	v_cmp_le_u32_e32 vcc, s15, v0
	s_bcnt1_i32_b64 s54, vcc
	s_cmp_eq_u32 s54, 16
	s_cbranch_scc1 .Lmy_rs_hit_p
	s_cmp_gt_u32 s54, 15
	s_cselect_b32 s16, s15, s16
	s_or_b32 s15, s16, 0x10000000
	v_cmp_le_u32_e32 vcc, s15, v0
	s_bcnt1_i32_b64 s54, vcc
	s_cmp_gt_u32 s54, 15
	s_cselect_b32 s16, s15, s16
	s_or_b32 s15, s16, 0x8000000
	v_cmp_le_u32_e32 vcc, s15, v0
	s_bcnt1_i32_b64 s54, vcc
	s_cmp_eq_u32 s54, 16
	s_cbranch_scc1 .Lmy_rs_hit_p
	s_cmp_gt_u32 s54, 15
	s_cselect_b32 s16, s15, s16
	s_or_b32 s15, s16, 0x4000000
	v_cmp_le_u32_e32 vcc, s15, v0
	s_bcnt1_i32_b64 s54, vcc
	s_cmp_gt_u32 s54, 15
	s_cselect_b32 s16, s15, s16
	s_or_b32 s15, s16, 0x2000000
	v_cmp_le_u32_e32 vcc, s15, v0
	s_bcnt1_i32_b64 s54, vcc
	s_cmp_eq_u32 s54, 16
	s_cbranch_scc1 .Lmy_rs_hit_p
	s_cmp_gt_u32 s54, 15
	s_cselect_b32 s16, s15, s16
	s_or_b32 s15, s16, 0x1000000
	v_cmp_le_u32_e32 vcc, s15, v0
	s_bcnt1_i32_b64 s54, vcc
	s_cmp_gt_u32 s54, 15
	s_cselect_b32 s16, s15, s16
	s_or_b32 s15, s16, 0x800000
	v_cmp_le_u32_e32 vcc, s15, v0
	s_bcnt1_i32_b64 s54, vcc
	s_cmp_eq_u32 s54, 16
	s_cbranch_scc1 .Lmy_rs_hit_p
	s_cmp_gt_u32 s54, 15
	s_cselect_b32 s16, s15, s16
	s_or_b32 s15, s16, 0x400000
	v_cmp_le_u32_e32 vcc, s15, v0
	s_bcnt1_i32_b64 s54, vcc
	s_cmp_gt_u32 s54, 15
	s_cselect_b32 s16, s15, s16
	s_or_b32 s15, s16, 0x200000
	v_cmp_le_u32_e32 vcc, s15, v0
	s_bcnt1_i32_b64 s54, vcc
	s_cmp_eq_u32 s54, 16
	s_cbranch_scc1 .Lmy_rs_hit_p
	s_cmp_gt_u32 s54, 15
	s_cselect_b32 s16, s15, s16
	s_or_b32 s15, s16, 0x100000
	v_cmp_le_u32_e32 vcc, s15, v0
	s_bcnt1_i32_b64 s54, vcc
	s_cmp_gt_u32 s54, 15
	s_cselect_b32 s16, s15, s16
	s_or_b32 s15, s16, 0x80000
	v_cmp_le_u32_e32 vcc, s15, v0
	s_bcnt1_i32_b64 s54, vcc
	s_cmp_eq_u32 s54, 16
	s_cbranch_scc1 .Lmy_rs_hit_p
	s_cmp_gt_u32 s54, 15
	s_cselect_b32 s16, s15, s16
	s_or_b32 s15, s16, 0x40000
	v_cmp_le_u32_e32 vcc, s15, v0
	s_bcnt1_i32_b64 s54, vcc
	s_cmp_gt_u32 s54, 15
	s_cselect_b32 s16, s15, s16
	s_or_b32 s15, s16, 0x20000
	v_cmp_le_u32_e32 vcc, s15, v0
	s_bcnt1_i32_b64 s54, vcc
	s_cmp_eq_u32 s54, 16
	s_cbranch_scc1 .Lmy_rs_hit_p
	s_cmp_gt_u32 s54, 15
	s_cselect_b32 s16, s15, s16
	s_or_b32 s15, s16, 0x10000
	v_cmp_le_u32_e32 vcc, s15, v0
	s_bcnt1_i32_b64 s54, vcc
	s_cmp_gt_u32 s54, 15
	s_cselect_b32 s16, s15, s16
	s_or_b32 s15, s16, 0x8000
	v_cmp_le_u32_e32 vcc, s15, v0
	s_bcnt1_i32_b64 s54, vcc
	s_cmp_eq_u32 s54, 16
	s_cbranch_scc1 .Lmy_rs_hit_p
	s_cmp_gt_u32 s54, 15
	s_cselect_b32 s16, s15, s16
	s_or_b32 s15, s16, 0x4000
	v_cmp_le_u32_e32 vcc, s15, v0
	s_bcnt1_i32_b64 s54, vcc
	s_cmp_gt_u32 s54, 15
	s_cselect_b32 s16, s15, s16
	s_or_b32 s15, s16, 0x2000
	v_cmp_le_u32_e32 vcc, s15, v0
	s_bcnt1_i32_b64 s54, vcc
	s_cmp_eq_u32 s54, 16
	s_cbranch_scc1 .Lmy_rs_hit_p
	s_cmp_gt_u32 s54, 15
	s_cselect_b32 s16, s15, s16
	s_or_b32 s15, s16, 0x1000
	v_cmp_le_u32_e32 vcc, s15, v0
	s_bcnt1_i32_b64 s54, vcc
	s_cmp_gt_u32 s54, 15
	s_cselect_b32 s16, s15, s16
	s_or_b32 s15, s16, 0x800
	v_cmp_le_u32_e32 vcc, s15, v0
	s_bcnt1_i32_b64 s54, vcc
	s_cmp_eq_u32 s54, 16
	s_cbranch_scc1 .Lmy_rs_hit_p
	s_cmp_gt_u32 s54, 15
	s_cselect_b32 s16, s15, s16
	s_or_b32 s15, s16, 0x400
	v_cmp_le_u32_e32 vcc, s15, v0
	s_bcnt1_i32_b64 s54, vcc
	s_cmp_gt_u32 s54, 15
	s_cselect_b32 s16, s15, s16
	s_or_b32 s15, s16, 0x200
	v_cmp_le_u32_e32 vcc, s15, v0
	s_bcnt1_i32_b64 s54, vcc
	s_cmp_eq_u32 s54, 16
	s_cbranch_scc1 .Lmy_rs_hit_p
	s_cmp_gt_u32 s54, 15
	s_cselect_b32 s16, s15, s16
	s_or_b32 s15, s16, 0x100
	v_cmp_le_u32_e32 vcc, s15, v0
	s_bcnt1_i32_b64 s54, vcc
	s_cmp_gt_u32 s54, 15
	s_cselect_b32 s16, s15, s16
	s_or_b32 s15, s16, 0x80
	v_cmp_le_u32_e32 vcc, s15, v0
	s_bcnt1_i32_b64 s54, vcc
	s_cmp_eq_u32 s54, 16
	s_cbranch_scc1 .Lmy_rs_hit_p
	s_cmp_gt_u32 s54, 15
	s_cselect_b32 s16, s15, s16
	s_or_b32 s15, s16, 64
	v_cmp_le_u32_e32 vcc, s15, v0
	s_bcnt1_i32_b64 s54, vcc
	s_cmp_gt_u32 s54, 15
	s_cselect_b32 s16, s15, s16
	s_or_b32 s15, s16, 32
	v_cmp_le_u32_e32 vcc, s15, v0
	s_bcnt1_i32_b64 s54, vcc
	s_cmp_eq_u32 s54, 16
	s_cbranch_scc1 .Lmy_rs_hit_p
	s_cmp_gt_u32 s54, 15
	s_cselect_b32 s16, s15, s16
	s_or_b32 s15, s16, 16
	v_cmp_le_u32_e32 vcc, s15, v0
	s_bcnt1_i32_b64 s54, vcc
	s_cmp_gt_u32 s54, 15
	s_cselect_b32 s16, s15, s16
	s_or_b32 s15, s16, 8
	v_cmp_le_u32_e32 vcc, s15, v0
	s_bcnt1_i32_b64 s54, vcc
	s_cmp_eq_u32 s54, 16
	s_cbranch_scc1 .Lmy_rs_hit_p
	s_cmp_gt_u32 s54, 15
	s_cselect_b32 s16, s15, s16
	s_or_b32 s15, s16, 4
	v_cmp_le_u32_e32 vcc, s15, v0
	s_bcnt1_i32_b64 s54, vcc
	s_cmp_gt_u32 s54, 15
	s_cselect_b32 s16, s15, s16
	s_or_b32 s15, s16, 2
	v_cmp_le_u32_e32 vcc, s15, v0
	s_bcnt1_i32_b64 s54, vcc
	s_cmp_eq_u32 s54, 16
	s_cbranch_scc1 .Lmy_rs_hit_p
	s_cmp_gt_u32 s54, 15
	s_cselect_b32 s16, s15, s16
	s_or_b32 s15, s16, 1
	v_cmp_le_u32_e32 vcc, s15, v0
	s_bcnt1_i32_b64 s54, vcc
	s_cmp_gt_u32 s54, 15
	s_cselect_b32 s16, s15, s16
	s_branch .Lmy_rs_go_p

; __device__ __forceinline__ void attn_prompt_unit(const AttnArgs& a, int n, int g, int qt, LAS unsigned char* lds, int tid) {
;     ...
;                     const unsigned long long gt = __ballot(key1 > thr1); unsigned long long eq = __ballot(key1 == thr1);
;                     int need = 16 - __popcll(gt); sel = gt;
.Lmy_rs_go_p:
	v_cmp_lt_u32_e64 s[14:15], s16, v0
	v_cmp_eq_u32_e64 s[16:17], s16, v0
	s_bcnt1_i32_b64 s54, s[14:15]
	s_cmp_eq_u64 s[16:17], 0
	v_cmp_gt_u64_e64 s[20:21], s[54:55], 15
	s_cselect_b64 s[22:23], -1, 0
	s_or_b64 s[20:21], s[20:21], s[22:23]
	s_and_b64 vcc, exec, s[20:21]
	s_cbranch_vccnz .LBB0_2804
	s_sub_i32 s19, 16, s54

; #define LAS __attribute__((address_space(3)))
; #define FB_ISSUE(T, S) do { __builtin_amdgcn_global_load_lds((const unsigned*)(ksrc + (size_t)(T) * 4096), (LAS unsigned*)(ring + (S) * A_SLOT), 16, 0, 0); \
;                             __builtin_amdgcn_global_load_lds((const unsigned*)(vsrc + (size_t)(T) * 4096), (LAS unsigned*)(ring + (S) * A_SLOT + 8192), 16, 0, 0); } while (0)
; template <int MODE> ...
;     asm volatile("" : "+v"(tid), "+v"(lane));
;     const int i = lane & 31, hh = lane >> 5; const int w = __builtin_amdgcn_readfirstlane(tid >> 6);
;     const bf16* ksrc = Kg + (size_t)lane * 64 + 8 * w;
;     const bf16* vsrc = Vg + (size_t)(16 * (w & 3) + (lane >> 2)) * 64 + 32 * (w >> 2) + 8 * (lane & 3);
;     LAS unsigned char* ring = lds + A_RING + w * 1024;
;     ...
;     float l = 0.f; bool seen = false;
;     f32x16 negm;
; #pragma unroll
;     for (int r = 0; r < 16; ++r) { o0[r] = 0.f; o1[r] = 0.f; negm[r] = 0.f; }
;     asm volatile("s_waitcnt vmcnt(0)" ::: "memory");
;     FB_ISSUE(tile_lo, 0); if (tile_lo < tile_hi) FB_ISSUE(tile_lo + 1, 1);
; __device__ __forceinline__ void attn_prompt_unit(const AttnArgs& a, int n, int g, int qt, LAS unsigned char* lds, int tid) {
;     ...
;         mlane = maskb[tau];
;     }
;     { int tq = t, hq = h, hhq = hh; asm volatile("" : "+v"(tq), "+v"(hq), "+v"(hhq));
;       const bf16* qp = a.QR + ((size_t)n * SEQ + tq) * D + (4 * g + hq) * 64 + 8 * hhq;
; #pragma unroll
;       for (int st = 0; st < 4; ++st) qf[st] = *(const bf16x8*)(qp + 16 * st); }
.LBB0_2807:
	v_lshl_add_u32 v0, v99, 3, v6
	ds_read_b64 v[136:137], v0
	v_mov_b32_e32 v2, v222
	v_mov_b32_e32 v0, v216
	s_ashr_i32 s29, s28, 31
	v_ashrrev_i32_e32 v3, 31, v2
	v_lshl_add_u64 v[2:3], s[26:27], 0, v[2:3]
	v_lshlrev_b64 v[2:3], 11, v[2:3]
	v_lshl_add_u32 v4, v98, 6, s85
	v_lshl_add_u64 v[2:3], s[50:51], 0, v[2:3]
	v_ashrrev_i32_e32 v5, 31, v4
	v_lshl_add_u64 v[2:3], v[4:5], 1, v[2:3]
	v_lshlrev_b32_e32 v4, 3, v0
	s_lshl_b64 s[0:1], s[28:29], 19
	v_readlane_b32 s8, v254, 36
	v_ashrrev_i32_e32 v5, 31, v4
	s_add_u32 s8, s8, s0
	v_readlane_b32 s9, v254, 38
	v_lshl_add_u64 v[2:3], v[4:5], 1, v[2:3]
	s_addc_u32 s9, s9, s1
	v_readlane_b32 s10, v254, 42
	v_mov_b32_e32 v4, v134
	v_mov_b32_e32 v0, v135
	s_add_u32 s14, s10, s0
	v_readlane_b32 s10, v254, 40
	s_addc_u32 s15, s10, s1
	v_readfirstlane_b32 s12, v0
	s_ashr_i32 s16, s12, 6
	s_lshl_b32 s13, s16, 4
	s_and_b32 s13, s13, 48
	v_ashrrev_i32_e32 v0, 2, v4
	v_ashrrev_i32_e32 v5, 31, v4
	v_add_u32_e32 v6, s13, v0
	v_lshlrev_b64 v[2:3], 7, v[4:5]
	s_lshl_b32 s10, s16, 3
	v_ashrrev_i32_e32 v7, 31, v6
	s_ashr_i32 s12, s12, 3
	s_lshl_b32 s16, s16, 10
	s_ashr_i32 s11, s10, 31
	v_lshlrev_b64 v[6:7], 7, v[6:7]
	s_andn2_b32 s12, s12, 31
	v_lshlrev_b32_e32 v0, 3, v4
	v_lshl_add_u64 v[8:9], s[8:9], 0, v[2:3]
	s_add_i32 s8, s16, 0
	s_ashr_i32 s13, s12, 31
	v_and_b32_e32 v5, 24, v0
	v_lshl_add_u64 v[138:139], s[10:11], 1, v[8:9]
	v_lshl_add_u64 v[8:9], s[14:15], 0, v[6:7]
	s_add_i32 s24, s8, 0x10000
	v_lshl_add_u64 v[8:9], s[12:13], 1, v[8:9]
	v_lshlrev_b32_e32 v0, 1, v5
	s_waitcnt vmcnt(0)
	s_mov_b32 m0, s24
	v_lshl_add_u64 v[140:141], v[8:9], 0, v[0:1]
	global_load_lds_dwordx4 v[138:139], off
	s_add_i32 m0, s8, 0x12000
	s_cmp_lg_u32 s84, 0
	global_load_lds_dwordx4 v[140:141], off
	s_cselect_b64 s[14:15], -1, 0
	s_cmp_eq_u32 s84, 0
	s_cbranch_scc1 .LBB0_2809
	s_add_i32 s8, s24, 0x6000
	s_add_i32 m0, s24, 0x4000
	v_lshl_add_u64 v[10:11], v[138:139], 0, s[82:83]
	v_lshl_add_u64 v[8:9], v[140:141], 0, s[82:83]
	global_load_lds_dwordx4 v[10:11], off
	s_mov_b32 m0, s8
	s_nop 0
	global_load_lds_dwordx4 v[8:9], off
